# EpiStoreN epilogues (in-proj both halves, FFN-up): the tile's row-stat block and bias slice are fetched by LDS-DMA into static LDS one tile ahead and read with ds_read_b128 instead of 12 exposed globa
# speedup vs baseline: 1.0594x; 1.0030x over previous
; #define PG8_STAGE(bufoff, gbase, voff) do { _Pragma("unroll") for (int _i = 0; _i < 2; ++_i) \
;         __builtin_amdgcn_global_load_lds((const unsigned*)((const char*)(gbase) + (voff)[_i]), (PG8_LAS unsigned*)(lds + (bufoff) + ldsw + _i * 8192), 16, 0, 0); } while (0)
; #define PG8_WAIT_V(n) asm volatile("s_waitcnt vmcnt(" #n ")" ::: "memory")
; #define PG8_BAR __builtin_amdgcn_s_barrier()
; template <class Epi, class Sched, bool ALIGN_EPI = false, bool SP2 = false>
; __device__ __forceinline__ void gemm_phase(PG8_LAS unsigned char* lds, const Gemm g, const Sched& S, const Epi& E) {
;     ...
;     for (int i = 0; i < 2; ++i) { int R, C; stage_rc(tid * 16 + i * 8192, R, C); const int Rb = Epi::PERM ? ((R & ~31) + perm32(R & 31)) : R;
;         voffA[i] = (unsigned)(R * K + C) * 2u; voffB[i] = (unsigned)(Rb * K + C) * 2u; }
;     const size_t kstep = (size_t)(BK * 2);
;     const size_t hstep = (size_t)HALF * K * 2;
;     const size_t tstep = 2 * hstep;
;     const unsigned ldsw = (unsigned)wid * 1024u;
;     const int aoff = lds_byte(wr * 64 + fr, fq * 8), boff = lds_byte(wc * 32 + fr, fq * 8);
;     ...
;         PG8_STAGE(PG8_SB(1, 0), cB + kstep, voffB); PG8_STAGE(PG8_SA(1, 0), cA + kstep, voffA); PG8_STAGE(PG8_SB(1, 1), cB + hstep + kstep, voffB);
;         PG8_WAIT_V(6); PG8_BAR;
.LBB0_156:
	v_readlane_b32 s10, v250, 19
	s_add_u32 s20, s24, 0x1c1d8000
	s_mul_i32 s0, s10, 0x18c00
	s_addc_u32 s21, s25, 0
	s_lshl_b64 s[34:35], s[0:1], 2
	s_add_u32 s0, s24, s34
	s_addc_u32 s10, s25, s35
	v_bfe_u32 v20, v16, 4, 2
	s_add_u32 s0, s0, 0x3a724000
	v_and_b32_e32 v17, 15, v16
	v_lshlrev_b32_e32 v18, 4, v20
	v_lshlrev_b32_e32 v16, 2, v16
	s_addc_u32 s51, s10, 0
	v_lshl_or_b32 v182, s26, 6, v17
	v_lshl_or_b32 v17, v17, 6, v18
	s_lshl_b32 s10, s26, 13
	v_and_b32_e32 v16, 32, v16
	v_bitop3_b32 v21, v17, s10, v16 bitop3:0xde
	s_lshl_b32 s10, s23, 5
	v_readlane_b32 s11, v250, 20
	s_and_b32 s10, s10, 0x60
	s_add_i32 m0, s7, 0x18000
	v_lshl_add_u64 v[8:9], v[8:9], 0, s[28:29]
	s_lshl_b32 s11, s10, 7
	s_waitcnt vmcnt(2)
	s_barrier
	global_load_lds_dwordx4 v[8:9], off
	v_lshl_add_u64 v[6:7], v[6:7], 0, s[28:29]
	s_add_i32 m0, s7, 0x1a000
	s_add_i32 s52, s7, 0x8000
	s_add_i32 s53, s7, 0xa000
	global_load_lds_dwordx4 v[6:7], off
	v_lshl_add_u64 v[2:3], v[2:3], 0, s[28:29]
	s_mov_b32 m0, s52
	s_add_u32 s26, s44, 0x40080
	global_load_lds_dwordx4 v[2:3], off
	v_lshl_add_u64 v[2:3], v[4:5], 0, s[28:29]
	s_mov_b32 m0, s53
	s_addc_u32 s27, s45, 0
	global_load_lds_dwordx4 v[2:3], off
	s_add_i32 m0, s7, 0x1c000
	v_lshl_add_u64 v[2:3], s[26:27], 0, v[0:1]
	global_load_lds_dwordx4 v[2:3], off
	v_lshl_add_u64 v[2:3], s[26:27], 0, v[146:147]
	s_add_i32 m0, s7, 0x1e000
	v_mov_b32_e32 v19, v1
	global_load_lds_dwordx4 v[2:3], off
	v_lshl_add_u64 v[2:3], s[24:25], 0, v[18:19]
	s_mov_b64 s[24:25], 0x3a8b0000
	v_lshl_add_u64 v[152:153], v[2:3], 0, s[24:25]
	v_lshlrev_b32_e32 v2, 14, v10
	v_and_b32_e32 v2, 0xffff8000, v2
	v_lshl_add_u32 v2, v11, 11, v2
	v_and_b32_e32 v3, 1, v10
	v_lshl_or_b32 v2, v3, 6, v2
	v_lshl_add_u32 v154, v12, 1, v2
	v_lshlrev_b32_e32 v2, 14, v14
	v_and_b32_e32 v2, 0xffff8000, v2
	s_waitcnt vmcnt(6)
	v_lshl_add_u32 v2, v13, 11, v2
	v_and_b32_e32 v3, 1, v14
	v_bitop3_b32 v183, v17, s11, v16 bitop3:0xde
	s_cmpk_lt_u32 s22, 0x100
	v_lshl_or_b32 v184, v20, 3, s10
	v_lshl_or_b32 v2, v3, 6, v2
	v_readlane_b32 s10, v251, 26
	s_cselect_b64 s[22:23], -1, 0
	v_mov_b32_e32 v155, v1
	v_lshl_add_u32 v156, v15, 1, v2
	v_mov_b32_e32 v157, v1
	s_mov_b32 s54, 0
	v_add_u32_e32 v185, 16, v21
	v_readlane_b32 s55, v251, 23
	s_mov_b32 s56, s10
	v_lshlrev_b32_e32 v244, 4, v228
	v_readfirstlane_b32 s98, v163
	v_readfirstlane_b32 s100, v152
	v_readfirstlane_b32 s101, v153
	s_lshl_b32 s98, s98, 5
	s_lshl_b32 s99, 0x8000, 6
	s_lshl_b32 s32, s56, 14
	s_add_i32 s99, s99, s32
	s_add_i32 s99, s99, s98
	s_add_u32 s100, s100, s99
	s_addc_u32 s101, s101, 0
	s_add_i32 m0, s98, 0x20010
	s_nop 0
	global_load_lds_dwordx4 v244, s[100:101]
	global_load_lds_dwordx4 v244, s[100:101] offset:1024
	s_lshl_b32 s99, s56, 8
	s_add_i32 s99, s99, 0x8000
	s_min_i32 s99, s99, 0x10000
	s_ashr_i32 s99, s99, 13
	s_mulk_i32 s99, 0x1600
	s_lshl_b32 s99, s99, 2
	s_lshl_b32 s32, s55, 10
	s_add_i32 s99, s99, s32
	s_add_u32 s100, s0, s99
	s_addc_u32 s101, s51, 0
	s_mov_b32 m0, 0x24010
	s_nop 0
	global_load_lds_dwordx4 v244, s[100:101]
	s_barrier
	v_readlane_b32 s11, v251, 27
	s_branch .LBB0_159

; template <class Epi, class Sched, bool ALIGN_EPI = false, bool SP2 = false>
; __device__ __forceinline__ void gemm_phase(PG8_LAS unsigned char* lds, const Gemm g, const Sched& S, const Epi& E) {
;     ...
;         const bool has_next = S.next(ui + 1, nxt);
;         const char* nA = has_next ? (const char*)g.A + (size_t)nxt.pm * tstep : cA; const char* nB = has_next ? (const char*)g.Bt + (size_t)nxt.pn * tstep : cB;
;     ...
; #pragma unroll
;         for (int a = 0; a < 2; ++a)
; #pragma unroll
;             for (int b = 0; b < 2; ++b)
; #pragma unroll
;                 for (int m = 0; m < 4; ++m)
; #pragma unroll
;                     for (int n = 0; n < 2; ++n) acc[a][b][m][n] = (f32x4){0.f, 0.f, 0.f, 0.f};
;         cur = nxt; cA = nA; cB = nB; ++ui;
.LBB0_161:
	s_and_b64 s[98:99], s[38:39], exec
	s_cselect_b32 s71, s26, s56
	s_cselect_b32 s73, s24, s55
	s_ashr_i32 s27, s26, 31
	s_lshl_b64 s[34:35], s[26:27], 19
	s_add_u32 s40, s2, s34
	s_addc_u32 s41, s3, s35
	s_and_b64 s[34:35], s[38:39], exec
	s_cselect_b32 s27, s41, s47
	s_cselect_b32 s34, s40, s46
	s_ashr_i32 s25, s24, 31
	s_lshl_b64 s[42:43], s[24:25], 19
	s_add_u32 s42, s4, s42
	s_addc_u32 s43, s5, s43
	s_and_b64 s[48:49], s[38:39], exec
	s_cselect_b32 s25, s43, s45
	s_cselect_b32 s35, s42, s44
	s_add_u32 s57, s44, 0x100
	s_addc_u32 s58, s45, 0
	s_add_u32 s44, s46, 0x40080
	v_mov_b32_e32 v2, 0
	s_addc_u32 s45, s47, 0
	s_mov_b32 s59, -2
	v_mov_b32_e32 v3, v2
	v_mov_b32_e32 v4, v2
	v_mov_b32_e32 v5, v2
	v_mov_b32_e32 v6, v2
	v_mov_b32_e32 v7, v2
	v_mov_b32_e32 v8, v2
	v_mov_b32_e32 v9, v2
	v_mov_b32_e32 v18, v2
	v_mov_b32_e32 v19, v2
	v_mov_b32_e32 v20, v2
	v_mov_b32_e32 v21, v2
	v_mov_b32_e32 v22, v2
	v_mov_b32_e32 v23, v2
	v_mov_b32_e32 v24, v2
	v_mov_b32_e32 v25, v2
	v_mov_b32_e32 v34, v2
	v_mov_b32_e32 v35, v2
	v_mov_b32_e32 v36, v2
	v_mov_b32_e32 v37, v2
	v_mov_b32_e32 v38, v2
	v_mov_b32_e32 v39, v2
	v_mov_b32_e32 v40, v2
	v_mov_b32_e32 v41, v2
	v_mov_b32_e32 v50, v2
	v_mov_b32_e32 v51, v2
	v_mov_b32_e32 v52, v2
	v_mov_b32_e32 v53, v2
	v_mov_b32_e32 v54, v2
	v_mov_b32_e32 v55, v2
	v_mov_b32_e32 v56, v2
	v_mov_b32_e32 v57, v2
	v_mov_b32_e32 v10, v2
	v_mov_b32_e32 v11, v2
	v_mov_b32_e32 v12, v2
	v_mov_b32_e32 v13, v2
	v_mov_b32_e32 v14, v2
	v_mov_b32_e32 v15, v2
	v_mov_b32_e32 v16, v2
	v_mov_b32_e32 v17, v2
	v_mov_b32_e32 v26, v2
	v_mov_b32_e32 v27, v2
	v_mov_b32_e32 v28, v2
	v_mov_b32_e32 v29, v2
	v_mov_b32_e32 v30, v2
	v_mov_b32_e32 v31, v2
	v_mov_b32_e32 v32, v2
	v_mov_b32_e32 v33, v2
	v_mov_b32_e32 v42, v2
	v_mov_b32_e32 v43, v2
	v_mov_b32_e32 v44, v2
	v_mov_b32_e32 v45, v2
	v_mov_b32_e32 v46, v2
	v_mov_b32_e32 v47, v2
	v_mov_b32_e32 v48, v2
	v_mov_b32_e32 v49, v2
	v_mov_b32_e32 v58, v2
	v_mov_b32_e32 v59, v2
	v_mov_b32_e32 v60, v2
	v_mov_b32_e32 v61, v2
	v_mov_b32_e32 v62, v2
	v_mov_b32_e32 v63, v2
	v_mov_b32_e32 v64, v2
	v_mov_b32_e32 v65, v2
	v_mov_b32_e32 v66, v2
	v_mov_b32_e32 v67, v2
	v_mov_b32_e32 v68, v2
	v_mov_b32_e32 v69, v2
	v_mov_b32_e32 v70, v2
	v_mov_b32_e32 v71, v2
	v_mov_b32_e32 v72, v2
	v_mov_b32_e32 v73, v2
	v_mov_b32_e32 v82, v2
	v_mov_b32_e32 v83, v2
	v_mov_b32_e32 v84, v2
	v_mov_b32_e32 v85, v2
	v_mov_b32_e32 v86, v2
	v_mov_b32_e32 v87, v2
	v_mov_b32_e32 v88, v2
	v_mov_b32_e32 v89, v2
	v_mov_b32_e32 v114, v2
	v_mov_b32_e32 v115, v2
	v_mov_b32_e32 v116, v2
	v_mov_b32_e32 v117, v2
	v_mov_b32_e32 v118, v2
	v_mov_b32_e32 v119, v2
	v_mov_b32_e32 v120, v2
	v_mov_b32_e32 v121, v2
	v_mov_b32_e32 v130, v2
	v_mov_b32_e32 v131, v2
	v_mov_b32_e32 v132, v2
	v_mov_b32_e32 v133, v2
	v_mov_b32_e32 v134, v2
	v_mov_b32_e32 v135, v2
	v_mov_b32_e32 v136, v2
	v_mov_b32_e32 v137, v2
	v_mov_b32_e32 v74, v2
	v_mov_b32_e32 v75, v2
	v_mov_b32_e32 v76, v2
	v_mov_b32_e32 v77, v2
	v_mov_b32_e32 v78, v2
	v_mov_b32_e32 v79, v2
	v_mov_b32_e32 v80, v2
	v_mov_b32_e32 v81, v2
	v_mov_b32_e32 v106, v2
	v_mov_b32_e32 v107, v2
	v_mov_b32_e32 v108, v2
	v_mov_b32_e32 v109, v2
	v_mov_b32_e32 v110, v2
	v_mov_b32_e32 v111, v2
	v_mov_b32_e32 v112, v2
	v_mov_b32_e32 v113, v2
	v_mov_b32_e32 v122, v2
	v_mov_b32_e32 v123, v2
	v_mov_b32_e32 v124, v2
	v_mov_b32_e32 v125, v2
	v_mov_b32_e32 v126, v2
	v_mov_b32_e32 v127, v2
	v_mov_b32_e32 v128, v2
	v_mov_b32_e32 v129, v2
	v_mov_b32_e32 v138, v2
	v_mov_b32_e32 v139, v2
	v_mov_b32_e32 v140, v2
	v_mov_b32_e32 v141, v2
	v_mov_b32_e32 v142, v2
	v_mov_b32_e32 v143, v2
	v_mov_b32_e32 v144, v2
	v_mov_b32_e32 v145, v2

; __device__ __forceinline__ unsigned pk2(float lo, float hi) { return pg8::cvt_pk_bf16(lo, hi); }
;     __device__ __forceinline__ void operator()(const f32x4 (&acc)[2][2][4][2], const pg8::Unit& u, int wr, int wc, int fr, int fq) const {
;         const int row0 = u.pm * 256 + wr * 64 + fr, col0 = u.pn * 256 + wc * 32 + 8 * fq;
;         const int Rt = rowbase + u.pm * 256;
;         const float* bp = bias + (size_t)(Rt < TL ? (Rt >> 13) : 8) * FF2 + col0;
;         f32x4 bv[2][2];
; #pragma unroll
;         for (int bj = 0; bj < 2; ++bj) { bv[bj][0] = *(const f32x4*)(bp + bj * 128); bv[bj][1] = *(const f32x4*)(bp + bj * 128 + 4); }
; #pragma unroll
;         for (int ai = 0; ai < 2; ++ai)
; #pragma unroll
;             for (int m = 0; m < 4; ++m) { const int r = row0 + ai * 128 + m * 16, Rg = rowbase + r;
;                 const f32x4 q = *(const f32x4*)(stat + (size_t)Rg * 16 + fq * 4);
;                 float ssq = (q[0] + q[1]) + (q[2] + q[3]); ssq += __shfl_xor(ssq, 16); ssq += __shfl_xor(ssq, 32);
;                 const float rstd = rsqrtf(ssq * (1.f / DM) + 1e-6f);
;                 bf16_t* rowp = O + (size_t)r * ldc + col0;
; #pragma unroll
;                 for (int bj = 0; bj < 2; ++bj) { const f32x4 v0 = acc[ai][bj][m][0] * rstd + bv[bj][0], v1 = acc[ai][bj][m][1] * rstd + bv[bj][1];
;                     u32x4 w; w.x = pk2(v0[0], v0[1]); w.y = pk2(v0[2], v0[3]); w.z = pk2(v1[0], v1[1]); w.w = pk2(v1[2], v1[3]);
;                     *(u32x4*)(rowp + bj * 128) = w; } }
.LBB0_165:
	v_and_b32_e32 v160, 64, v228
	v_xor_b32_e32 v159, 16, v228
	v_add_u32_e32 v160, 64, v160
	s_lshl_b32 s10, s56, 8
	v_cmp_lt_i32_e32 vcc, v159, v160
	s_min_i32 s11, s10, 0x8000
	s_add_i32 s11, s11, 0x8000
	v_cndmask_b32_e32 v159, v228, v159, vcc
	v_lshlrev_b32_e32 v186, 2, v159
	v_xor_b32_e32 v159, 32, v228
	s_ashr_i32 s11, s11, 13
	v_cmp_lt_i32_e32 vcc, v159, v160
	s_mul_i32 s34, s11, 0x1600
	v_add_u32_e32 v158, s10, v182
	v_cndmask_b32_e32 v159, v228, v159, vcc
	s_ashr_i32 s35, s34, 31
	v_lshlrev_b32_e32 v187, 2, v159
	v_ashrrev_i32_e32 v159, 31, v158
	s_lshl_b64 s[34:35], s[34:35], 2
	v_lshlrev_b64 v[160:161], 6, v[158:159]
	v_lshl_or_b32 v176, s55, 8, v184
	s_add_u32 s34, s0, s34
	v_lshl_add_u64 v[178:179], v[152:153], 0, v[160:161]
	s_mov_b32 s10, 0x200000
	s_addc_u32 s35, s51, s35
	v_ashrrev_i32_e32 v177, 31, v176
	v_add_co_u32_e32 v180, vcc, s10, v178
	v_lshl_add_u64 v[94:95], v[176:177], 2, s[34:35]
	s_nop 0
	v_addc_co_u32_e32 v181, vcc, 0, v179, vcc
	v_lshlrev_b32_e32 v195, 2, v184
	v_add_u32_e32 v195, 0x24010, v195
	ds_read_b128 v[98:101], v195 offset:16
	ds_read_b128 v[102:105], v195
	ds_read_b128 v[90:93], v195 offset:528
	ds_read_b128 v[94:97], v195 offset:512
	v_lshlrev_b64 v[176:177], 1, v[176:177]
	v_lshlrev_b32_e32 v194, 6, v182
	v_and_b32_e32 v195, 48, v163
	v_add_u32_e32 v194, v194, v195
	v_add_u32_e32 v194, 0x20010, v194
	ds_read_b128 v[188:191], v194
	ds_read_b128 v[196:199], v194 offset:1024
	ds_read_b128 v[200:203], v194 offset:2048
	ds_read_b128 v[204:207], v194 offset:3072
	ds_read_b128 v[208:211], v194 offset:8192
	ds_read_b128 v[212:215], v194 offset:9216
	ds_read_b128 v[216:219], v194 offset:10240
	ds_read_b128 v[220:223], v194 offset:11264
	s_mov_b32 s10, 0x202000
	s_mov_b64 s[44:45], -1
	s_waitcnt vmcnt(0) lgkmcnt(0)
	s_barrier
	v_lshlrev_b32_e32 v244, 4, v228
	v_readfirstlane_b32 s98, v163
	v_readfirstlane_b32 s100, v152
	v_readfirstlane_b32 s101, v153
	s_lshl_b32 s98, s98, 5
	s_lshl_b32 s99, 0x8000, 6
	s_lshl_b32 s32, s71, 14
	s_add_i32 s99, s99, s32
	s_add_i32 s99, s99, s98
	s_add_u32 s100, s100, s99
	s_addc_u32 s101, s101, 0
	s_add_i32 m0, s98, 0x20010
	s_nop 0
	global_load_lds_dwordx4 v244, s[100:101]
	global_load_lds_dwordx4 v244, s[100:101] offset:1024
	s_lshl_b32 s99, s71, 8
	s_add_i32 s99, s99, 0x8000
	s_min_i32 s99, s99, 0x10000
	s_ashr_i32 s99, s99, 13
	s_mulk_i32 s99, 0x1600
	s_lshl_b32 s99, s99, 2
	s_lshl_b32 s32, s73, 10
	s_add_i32 s99, s99, s32
	s_add_u32 s100, s0, s99
	s_addc_u32 s101, s51, 0
	s_mov_b32 m0, 0x24010
	s_nop 0
	global_load_lds_dwordx4 v244, s[100:101]
	v_mov_b32_e32 v160, v189
	v_mov_b32_e32 v161, v190
	v_mov_b32_e32 v189, v191
	v_pk_add_f32 v[160:161], v[160:161], v[188:189]
	s_nop 0
	v_add_f32_e32 v159, v160, v161
	ds_bpermute_b32 v160, v186, v159
	s_waitcnt lgkmcnt(0)
	v_add_f32_e32 v159, v159, v160
	ds_bpermute_b32 v160, v187, v159
	s_waitcnt lgkmcnt(0)
	v_add_f32_e32 v159, v159, v160
	v_fmamk_f32 v159, v159, 0x3a800000, v162
	v_cmp_gt_f32_e32 vcc, s82, v159
	v_mul_f32_e32 v160, 0x4b800000, v159
	s_nop 0
	v_cndmask_b32_e32 v159, v159, v160, vcc
	v_rsq_f32_e32 v159, v159
	s_nop 0
	v_mul_f32_e32 v160, 0x45800000, v159
	v_cndmask_b32_e32 v188, v159, v160, vcc
	v_mov_b64_e32 v[160:161], s[20:21]
	v_mad_i64_i32 v[190:191], s[34:35], v158, s83, v[160:161]
	v_pk_fma_f32 v[144:145], v[144:145], v[188:189], v[104:105] op_sel_hi:[1,0,1]
	v_pk_fma_f32 v[142:143], v[142:143], v[188:189], v[102:103] op_sel_hi:[1,0,1]
	v_pk_fma_f32 v[192:193], v[140:141], v[188:189], v[100:101] op_sel_hi:[1,0,1]
	v_pk_fma_f32 v[140:141], v[138:139], v[188:189], v[98:99] op_sel_hi:[1,0,1]
	v_lshl_add_u64 v[190:191], v[190:191], 0, v[176:177]
	v_cvt_pk_bf16_f32 v138, v142, v143
	v_cvt_pk_bf16_f32 v139, v144, v145
	v_cvt_pk_bf16_f32 v140, v140, v141
	v_cvt_pk_bf16_f32 v141, v192, v193
	global_store_dwordx4 v[190:191], v[138:141], off
	v_pk_fma_f32 v[136:137], v[136:137], v[188:189], v[96:97] op_sel_hi:[1,0,1]
	v_pk_fma_f32 v[134:135], v[134:135], v[188:189], v[94:95] op_sel_hi:[1,0,1]
	v_pk_fma_f32 v[138:139], v[132:133], v[188:189], v[92:93] op_sel_hi:[1,0,1]
	v_pk_fma_f32 v[132:133], v[130:131], v[188:189], v[90:91] op_sel_hi:[1,0,1]
	v_cvt_pk_bf16_f32 v130, v134, v135
	v_cvt_pk_bf16_f32 v131, v136, v137
	v_cvt_pk_bf16_f32 v132, v132, v133
	v_cvt_pk_bf16_f32 v133, v138, v139
	global_store_dwordx4 v[190:191], v[130:133], off offset:256
	v_or_b32_e32 v136, 16, v158
	s_nop 1
	v_add_f32_e32 v130, v196, v197
	v_add_f32_e32 v131, v198, v199
	v_mad_i64_i32 v[132:133], s[34:35], v136, s83, v[160:161]
	v_add_f32_e32 v130, v130, v131
	ds_bpermute_b32 v131, v186, v130
	v_lshl_add_u64 v[132:133], v[132:133], 0, v[176:177]
	s_waitcnt lgkmcnt(0)
	v_add_f32_e32 v130, v130, v131
	ds_bpermute_b32 v131, v187, v130
	s_waitcnt lgkmcnt(0)
	v_add_f32_e32 v130, v130, v131
	v_fmamk_f32 v130, v130, 0x3a800000, v162
	v_cmp_gt_f32_e32 vcc, s82, v130
	v_mul_f32_e32 v131, 0x4b800000, v130
	s_nop 0
	v_cndmask_b32_e32 v130, v130, v131, vcc
	v_rsq_f32_e32 v130, v130
	s_nop 0
	v_mul_f32_e32 v131, 0x45800000, v130
	v_cndmask_b32_e32 v130, v130, v131, vcc
	v_pk_fma_f32 v[128:129], v[128:129], v[130:131], v[104:105] op_sel_hi:[1,0,1]
	v_pk_fma_f32 v[126:127], v[126:127], v[130:131], v[102:103] op_sel_hi:[1,0,1]
	v_pk_fma_f32 v[134:135], v[124:125], v[130:131], v[100:101] op_sel_hi:[1,0,1]
	v_pk_fma_f32 v[124:125], v[122:123], v[130:131], v[98:99] op_sel_hi:[1,0,1]
	v_cvt_pk_bf16_f32 v122, v126, v127
	v_cvt_pk_bf16_f32 v123, v128, v129
	v_cvt_pk_bf16_f32 v124, v124, v125
	v_cvt_pk_bf16_f32 v125, v134, v135
	global_store_dwordx4 v[132:133], v[122:125], off
	v_pk_fma_f32 v[120:121], v[120:121], v[130:131], v[96:97] op_sel_hi:[1,0,1]
	v_pk_fma_f32 v[118:119], v[118:119], v[130:131], v[94:95] op_sel_hi:[1,0,1]
	v_pk_fma_f32 v[122:123], v[116:117], v[130:131], v[92:93] op_sel_hi:[1,0,1]
	v_pk_fma_f32 v[116:117], v[114:115], v[130:131], v[90:91] op_sel_hi:[1,0,1]
	v_cvt_pk_bf16_f32 v114, v118, v119
	v_cvt_pk_bf16_f32 v115, v120, v121
	v_cvt_pk_bf16_f32 v116, v116, v117
	v_cvt_pk_bf16_f32 v117, v122, v123
	global_store_dwordx4 v[132:133], v[114:117], off offset:256
	v_or_b32_e32 v120, 32, v158
	s_nop 1
	v_add_f32_e32 v114, v200, v201
	v_add_f32_e32 v115, v202, v203
	v_mad_i64_i32 v[116:117], s[34:35], v120, s83, v[160:161]
	v_add_f32_e32 v114, v114, v115
	ds_bpermute_b32 v115, v186, v114
	v_lshl_add_u64 v[116:117], v[116:117], 0, v[176:177]
	s_waitcnt lgkmcnt(0)
; __device__ __forceinline__ unsigned pk2(float lo, float hi) { return pg8::cvt_pk_bf16(lo, hi); }
;     __device__ __forceinline__ void operator()(const f32x4 (&acc)[2][2][4][2], const pg8::Unit& u, int wr, int wc, int fr, int fq) const {
;     ...
;             for (int m = 0; m < 4; ++m) { const int r = row0 + ai * 128 + m * 16, Rg = rowbase + r;
;                 const f32x4 q = *(const f32x4*)(stat + (size_t)Rg * 16 + fq * 4);
;                 float ssq = (q[0] + q[1]) + (q[2] + q[3]); ssq += __shfl_xor(ssq, 16); ssq += __shfl_xor(ssq, 32);
;                 const float rstd = rsqrtf(ssq * (1.f / DM) + 1e-6f);
;                 bf16_t* rowp = O + (size_t)r * ldc + col0;
; #pragma unroll
;                 for (int bj = 0; bj < 2; ++bj) { const f32x4 v0 = acc[ai][bj][m][0] * rstd + bv[bj][0], v1 = acc[ai][bj][m][1] * rstd + bv[bj][1];
;                     u32x4 w; w.x = pk2(v0[0], v0[1]); w.y = pk2(v0[2], v0[3]); w.z = pk2(v1[0], v1[1]); w.w = pk2(v1[2], v1[3]);
;                     *(u32x4*)(rowp + bj * 128) = w; } }
	v_add_f32_e32 v114, v114, v115
	ds_bpermute_b32 v115, v187, v114
	s_waitcnt lgkmcnt(0)
	v_add_f32_e32 v114, v114, v115
	v_fmamk_f32 v114, v114, 0x3a800000, v162
	v_cmp_gt_f32_e32 vcc, s82, v114
	v_mul_f32_e32 v115, 0x4b800000, v114
	s_nop 0
	v_cndmask_b32_e32 v114, v114, v115, vcc
	v_rsq_f32_e32 v114, v114
	s_nop 0
	v_mul_f32_e32 v115, 0x45800000, v114
	v_cndmask_b32_e32 v114, v114, v115, vcc
	v_pk_fma_f32 v[112:113], v[112:113], v[114:115], v[104:105] op_sel_hi:[1,0,1]
	v_pk_fma_f32 v[110:111], v[110:111], v[114:115], v[102:103] op_sel_hi:[1,0,1]
	v_pk_fma_f32 v[118:119], v[108:109], v[114:115], v[100:101] op_sel_hi:[1,0,1]
	v_pk_fma_f32 v[108:109], v[106:107], v[114:115], v[98:99] op_sel_hi:[1,0,1]
	v_cvt_pk_bf16_f32 v106, v110, v111
	v_cvt_pk_bf16_f32 v107, v112, v113
	v_cvt_pk_bf16_f32 v108, v108, v109
	v_cvt_pk_bf16_f32 v109, v118, v119
	global_store_dwordx4 v[116:117], v[106:109], off
	v_pk_fma_f32 v[88:89], v[88:89], v[114:115], v[96:97] op_sel_hi:[1,0,1]
	v_pk_fma_f32 v[86:87], v[86:87], v[114:115], v[94:95] op_sel_hi:[1,0,1]
	v_pk_fma_f32 v[106:107], v[84:85], v[114:115], v[92:93] op_sel_hi:[1,0,1]
	v_pk_fma_f32 v[84:85], v[82:83], v[114:115], v[90:91] op_sel_hi:[1,0,1]
	v_cvt_pk_bf16_f32 v82, v86, v87
	v_cvt_pk_bf16_f32 v83, v88, v89
	v_cvt_pk_bf16_f32 v84, v84, v85
	v_cvt_pk_bf16_f32 v85, v106, v107
	global_store_dwordx4 v[116:117], v[82:85], off offset:256
	v_or_b32_e32 v88, 48, v158
	s_nop 1
	v_add_f32_e32 v82, v204, v205
	v_add_f32_e32 v83, v206, v207
	v_mad_i64_i32 v[84:85], s[34:35], v88, s83, v[160:161]
	v_add_f32_e32 v82, v82, v83
	ds_bpermute_b32 v83, v186, v82
	v_lshl_add_u64 v[84:85], v[84:85], 0, v[176:177]
	s_waitcnt lgkmcnt(0)
	v_add_f32_e32 v82, v82, v83
	ds_bpermute_b32 v83, v187, v82
	s_waitcnt lgkmcnt(0)
	v_add_f32_e32 v82, v82, v83
	v_fmamk_f32 v82, v82, 0x3a800000, v162
	v_cmp_gt_f32_e32 vcc, s82, v82
	v_mul_f32_e32 v83, 0x4b800000, v82
	s_nop 0
	v_cndmask_b32_e32 v82, v82, v83, vcc
	v_rsq_f32_e32 v82, v82
	s_nop 0
	v_mul_f32_e32 v83, 0x45800000, v82
	v_cndmask_b32_e32 v82, v82, v83, vcc
	v_pk_fma_f32 v[80:81], v[80:81], v[82:83], v[104:105] op_sel_hi:[1,0,1]
	v_pk_fma_f32 v[78:79], v[78:79], v[82:83], v[102:103] op_sel_hi:[1,0,1]
	v_pk_fma_f32 v[86:87], v[76:77], v[82:83], v[100:101] op_sel_hi:[1,0,1]
	v_pk_fma_f32 v[76:77], v[74:75], v[82:83], v[98:99] op_sel_hi:[1,0,1]
	v_cvt_pk_bf16_f32 v74, v78, v79
	v_cvt_pk_bf16_f32 v75, v80, v81
	v_cvt_pk_bf16_f32 v76, v76, v77
	v_cvt_pk_bf16_f32 v77, v86, v87
	global_store_dwordx4 v[84:85], v[74:77], off
	v_pk_fma_f32 v[72:73], v[72:73], v[82:83], v[96:97] op_sel_hi:[1,0,1]
	v_pk_fma_f32 v[70:71], v[70:71], v[82:83], v[94:95] op_sel_hi:[1,0,1]
	v_pk_fma_f32 v[74:75], v[68:69], v[82:83], v[92:93] op_sel_hi:[1,0,1]
	v_pk_fma_f32 v[68:69], v[66:67], v[82:83], v[90:91] op_sel_hi:[1,0,1]
	v_cvt_pk_bf16_f32 v66, v70, v71
	v_cvt_pk_bf16_f32 v67, v72, v73
	v_cvt_pk_bf16_f32 v68, v68, v69
	v_cvt_pk_bf16_f32 v69, v74, v75
	global_store_dwordx4 v[84:85], v[66:69], off offset:256
	v_add_u32_e32 v74, 0x80, v158
	s_nop 0
	v_add_co_u32_e32 v66, vcc, s10, v178
	s_nop 1
	v_addc_co_u32_e32 v67, vcc, 0, v179, vcc
	s_nop 1
	v_add_f32_e32 v68, v208, v209
	v_add_f32_e32 v69, v210, v211
	v_mad_i64_i32 v[70:71], s[34:35], v74, s83, v[160:161]
	v_add_f32_e32 v68, v68, v69
	ds_bpermute_b32 v69, v186, v68
	v_lshl_add_u64 v[70:71], v[70:71], 0, v[176:177]
	s_waitcnt lgkmcnt(0)
	v_add_f32_e32 v68, v68, v69
	ds_bpermute_b32 v69, v187, v68
	s_waitcnt lgkmcnt(0)
	v_add_f32_e32 v68, v68, v69
	v_fmamk_f32 v68, v68, 0x3a800000, v162
	v_cmp_gt_f32_e32 vcc, s82, v68
	v_mul_f32_e32 v69, 0x4b800000, v68
	s_nop 0
	v_cndmask_b32_e32 v68, v68, v69, vcc
	v_rsq_f32_e32 v68, v68
	s_nop 0
	v_mul_f32_e32 v69, 0x45800000, v68
	v_cndmask_b32_e32 v68, v68, v69, vcc
	v_pk_fma_f32 v[64:65], v[64:65], v[68:69], v[104:105] op_sel_hi:[1,0,1]
	v_pk_fma_f32 v[62:63], v[62:63], v[68:69], v[102:103] op_sel_hi:[1,0,1]
	v_pk_fma_f32 v[72:73], v[60:61], v[68:69], v[100:101] op_sel_hi:[1,0,1]
	v_pk_fma_f32 v[60:61], v[58:59], v[68:69], v[98:99] op_sel_hi:[1,0,1]
	v_cvt_pk_bf16_f32 v58, v62, v63
	v_cvt_pk_bf16_f32 v59, v64, v65
	v_cvt_pk_bf16_f32 v60, v60, v61
	v_cvt_pk_bf16_f32 v61, v72, v73
	global_store_dwordx4 v[70:71], v[58:61], off
	v_pk_fma_f32 v[56:57], v[56:57], v[68:69], v[96:97] op_sel_hi:[1,0,1]
	v_pk_fma_f32 v[54:55], v[54:55], v[68:69], v[94:95] op_sel_hi:[1,0,1]
	v_pk_fma_f32 v[58:59], v[52:53], v[68:69], v[92:93] op_sel_hi:[1,0,1]
	v_pk_fma_f32 v[52:53], v[50:51], v[68:69], v[90:91] op_sel_hi:[1,0,1]
	v_cvt_pk_bf16_f32 v50, v54, v55
	v_cvt_pk_bf16_f32 v51, v56, v57
	v_cvt_pk_bf16_f32 v52, v52, v53
	v_cvt_pk_bf16_f32 v53, v58, v59
	global_store_dwordx4 v[70:71], v[50:53], off offset:256
	v_add_u32_e32 v56, 0x90, v158
	s_nop 1
	v_add_f32_e32 v50, v212, v213
	v_add_f32_e32 v51, v214, v215
	v_mad_i64_i32 v[52:53], s[34:35], v56, s83, v[160:161]
	v_add_f32_e32 v50, v50, v51
	ds_bpermute_b32 v51, v186, v50
	v_lshl_add_u64 v[52:53], v[52:53], 0, v[176:177]
	s_waitcnt lgkmcnt(0)
; __device__ __forceinline__ unsigned pk2(float lo, float hi) { return pg8::cvt_pk_bf16(lo, hi); }
;     __device__ __forceinline__ void operator()(const f32x4 (&acc)[2][2][4][2], const pg8::Unit& u, int wr, int wc, int fr, int fq) const {
;     ...
;             for (int m = 0; m < 4; ++m) { const int r = row0 + ai * 128 + m * 16, Rg = rowbase + r;
;                 const f32x4 q = *(const f32x4*)(stat + (size_t)Rg * 16 + fq * 4);
;                 float ssq = (q[0] + q[1]) + (q[2] + q[3]); ssq += __shfl_xor(ssq, 16); ssq += __shfl_xor(ssq, 32);
;                 const float rstd = rsqrtf(ssq * (1.f / DM) + 1e-6f);
;                 bf16_t* rowp = O + (size_t)r * ldc + col0;
; #pragma unroll
;                 for (int bj = 0; bj < 2; ++bj) { const f32x4 v0 = acc[ai][bj][m][0] * rstd + bv[bj][0], v1 = acc[ai][bj][m][1] * rstd + bv[bj][1];
;                     u32x4 w; w.x = pk2(v0[0], v0[1]); w.y = pk2(v0[2], v0[3]); w.z = pk2(v1[0], v1[1]); w.w = pk2(v1[2], v1[3]);
;                     *(u32x4*)(rowp + bj * 128) = w; } }
	v_add_f32_e32 v50, v50, v51
	ds_bpermute_b32 v51, v187, v50
	s_waitcnt lgkmcnt(0)
	v_add_f32_e32 v50, v50, v51
	v_fmamk_f32 v50, v50, 0x3a800000, v162
	v_cmp_gt_f32_e32 vcc, s82, v50
	v_mul_f32_e32 v51, 0x4b800000, v50
	s_nop 0
	v_cndmask_b32_e32 v50, v50, v51, vcc
	v_rsq_f32_e32 v50, v50
	s_nop 0
	v_mul_f32_e32 v51, 0x45800000, v50
	v_cndmask_b32_e32 v50, v50, v51, vcc
	v_pk_fma_f32 v[48:49], v[48:49], v[50:51], v[104:105] op_sel_hi:[1,0,1]
	v_pk_fma_f32 v[46:47], v[46:47], v[50:51], v[102:103] op_sel_hi:[1,0,1]
	v_pk_fma_f32 v[54:55], v[44:45], v[50:51], v[100:101] op_sel_hi:[1,0,1]
	v_pk_fma_f32 v[44:45], v[42:43], v[50:51], v[98:99] op_sel_hi:[1,0,1]
	v_cvt_pk_bf16_f32 v42, v46, v47
	v_cvt_pk_bf16_f32 v43, v48, v49
	v_cvt_pk_bf16_f32 v44, v44, v45
	v_cvt_pk_bf16_f32 v45, v54, v55
	global_store_dwordx4 v[52:53], v[42:45], off
	v_pk_fma_f32 v[40:41], v[40:41], v[50:51], v[96:97] op_sel_hi:[1,0,1]
	v_pk_fma_f32 v[38:39], v[38:39], v[50:51], v[94:95] op_sel_hi:[1,0,1]
	v_pk_fma_f32 v[42:43], v[36:37], v[50:51], v[92:93] op_sel_hi:[1,0,1]
	v_pk_fma_f32 v[36:37], v[34:35], v[50:51], v[90:91] op_sel_hi:[1,0,1]
	v_cvt_pk_bf16_f32 v34, v38, v39
	v_cvt_pk_bf16_f32 v35, v40, v41
	v_cvt_pk_bf16_f32 v36, v36, v37
	v_cvt_pk_bf16_f32 v37, v42, v43
	global_store_dwordx4 v[52:53], v[34:37], off offset:256
	v_add_u32_e32 v40, 0xa0, v158
	s_nop 1
	v_add_f32_e32 v34, v216, v217
	v_add_f32_e32 v35, v218, v219
	v_mad_i64_i32 v[36:37], s[34:35], v40, s83, v[160:161]
	v_add_f32_e32 v34, v34, v35
	ds_bpermute_b32 v35, v186, v34
	v_lshl_add_u64 v[36:37], v[36:37], 0, v[176:177]
	s_waitcnt lgkmcnt(0)
	v_add_f32_e32 v34, v34, v35
	ds_bpermute_b32 v35, v187, v34
	s_waitcnt lgkmcnt(0)
	v_add_f32_e32 v34, v34, v35
	v_fmamk_f32 v34, v34, 0x3a800000, v162
	v_cmp_gt_f32_e32 vcc, s82, v34
	v_mul_f32_e32 v35, 0x4b800000, v34
	s_nop 0
	v_cndmask_b32_e32 v34, v34, v35, vcc
	v_rsq_f32_e32 v34, v34
	s_nop 0
	v_mul_f32_e32 v35, 0x45800000, v34
	v_cndmask_b32_e32 v34, v34, v35, vcc
	v_pk_fma_f32 v[32:33], v[32:33], v[34:35], v[104:105] op_sel_hi:[1,0,1]
	v_pk_fma_f32 v[30:31], v[30:31], v[34:35], v[102:103] op_sel_hi:[1,0,1]
	v_pk_fma_f32 v[38:39], v[28:29], v[34:35], v[100:101] op_sel_hi:[1,0,1]
	v_pk_fma_f32 v[28:29], v[26:27], v[34:35], v[98:99] op_sel_hi:[1,0,1]
	v_cvt_pk_bf16_f32 v26, v30, v31
	v_cvt_pk_bf16_f32 v27, v32, v33
	v_cvt_pk_bf16_f32 v28, v28, v29
	v_cvt_pk_bf16_f32 v29, v38, v39
	global_store_dwordx4 v[36:37], v[26:29], off
	v_pk_fma_f32 v[24:25], v[24:25], v[34:35], v[96:97] op_sel_hi:[1,0,1]
	v_pk_fma_f32 v[22:23], v[22:23], v[34:35], v[94:95] op_sel_hi:[1,0,1]
	v_pk_fma_f32 v[26:27], v[20:21], v[34:35], v[92:93] op_sel_hi:[1,0,1]
	v_pk_fma_f32 v[20:21], v[18:19], v[34:35], v[90:91] op_sel_hi:[1,0,1]
	v_cvt_pk_bf16_f32 v18, v22, v23
	v_cvt_pk_bf16_f32 v19, v24, v25
	v_cvt_pk_bf16_f32 v20, v20, v21
	v_cvt_pk_bf16_f32 v21, v26, v27
	global_store_dwordx4 v[36:37], v[18:21], off offset:256
	v_add_u32_e32 v24, 0xb0, v158
	s_nop 1
	v_add_f32_e32 v18, v220, v221
	v_add_f32_e32 v19, v222, v223
	v_mad_i64_i32 v[20:21], s[34:35], v24, s83, v[160:161]
	v_add_f32_e32 v18, v18, v19
	ds_bpermute_b32 v19, v186, v18
	v_lshl_add_u64 v[20:21], v[20:21], 0, v[176:177]
	s_waitcnt lgkmcnt(0)
	v_add_f32_e32 v18, v18, v19
	ds_bpermute_b32 v19, v187, v18
	s_waitcnt lgkmcnt(0)
	v_add_f32_e32 v18, v18, v19
	v_fmamk_f32 v18, v18, 0x3a800000, v162
	v_cmp_gt_f32_e32 vcc, s82, v18
	v_mul_f32_e32 v19, 0x4b800000, v18
	s_nop 0
	v_cndmask_b32_e32 v18, v18, v19, vcc
	v_rsq_f32_e32 v18, v18
	s_nop 0
	v_mul_f32_e32 v19, 0x45800000, v18
	v_cndmask_b32_e32 v18, v18, v19, vcc
	v_pk_fma_f32 v[16:17], v[16:17], v[18:19], v[104:105] op_sel_hi:[1,0,1]
	v_pk_fma_f32 v[14:15], v[14:15], v[18:19], v[102:103] op_sel_hi:[1,0,1]
	v_pk_fma_f32 v[22:23], v[12:13], v[18:19], v[100:101] op_sel_hi:[1,0,1]
	v_pk_fma_f32 v[12:13], v[10:11], v[18:19], v[98:99] op_sel_hi:[1,0,1]
	v_cvt_pk_bf16_f32 v10, v14, v15
	v_cvt_pk_bf16_f32 v11, v16, v17
	v_cvt_pk_bf16_f32 v12, v12, v13
	v_cvt_pk_bf16_f32 v13, v22, v23
	global_store_dwordx4 v[20:21], v[10:13], off
	v_pk_fma_f32 v[8:9], v[8:9], v[18:19], v[96:97] op_sel_hi:[1,0,1]
	v_pk_fma_f32 v[6:7], v[6:7], v[18:19], v[94:95] op_sel_hi:[1,0,1]
	v_pk_fma_f32 v[10:11], v[4:5], v[18:19], v[92:93] op_sel_hi:[1,0,1]
	v_pk_fma_f32 v[4:5], v[2:3], v[18:19], v[90:91] op_sel_hi:[1,0,1]
	v_cvt_pk_bf16_f32 v2, v6, v7
	v_cvt_pk_bf16_f32 v3, v8, v9
	v_cvt_pk_bf16_f32 v4, v4, v5
	v_cvt_pk_bf16_f32 v5, v10, v11
	s_andn2_b64 vcc, exec, s[38:39]
	global_store_dwordx4 v[20:21], v[2:5], off offset:256
	s_cbranch_vccnz .LBB0_158
	s_andn2_b64 vcc, exec, s[18:19]
	s_cbranch_vccnz .LBB0_157
	s_barrier
	s_branch .LBB0_157

; #define PG8_STAGE(bufoff, gbase, voff) do { _Pragma("unroll") for (int _i = 0; _i < 2; ++_i) \
;         __builtin_amdgcn_global_load_lds((const unsigned*)((const char*)(gbase) + (voff)[_i]), (PG8_LAS unsigned*)(lds + (bufoff) + ldsw + _i * 8192), 16, 0, 0); } while (0)
; #define PG8_WAIT_V(n) asm volatile("s_waitcnt vmcnt(" #n ")" ::: "memory")
; #define PG8_BAR __builtin_amdgcn_s_barrier()
; template <class Epi, class Sched, bool ALIGN_EPI = false, bool SP2 = false>
; __device__ __forceinline__ void gemm_phase(PG8_LAS unsigned char* lds, const Gemm g, const Sched& S, const Epi& E) {
;     ...
;     for (int i = 0; i < 2; ++i) { int R, C; stage_rc(tid * 16 + i * 8192, R, C); const int Rb = Epi::PERM ? ((R & ~31) + perm32(R & 31)) : R;
;         voffA[i] = (unsigned)(R * K + C) * 2u; voffB[i] = (unsigned)(Rb * K + C) * 2u; }
;     const size_t kstep = (size_t)(BK * 2);
;     const size_t hstep = (size_t)HALF * K * 2;
;     const size_t tstep = 2 * hstep;
;     const unsigned ldsw = (unsigned)wid * 1024u;
;     const int aoff = lds_byte(wr * 64 + fr, fq * 8), boff = lds_byte(wc * 32 + fr, fq * 8);
;     ...
;         PG8_STAGE(PG8_SB(1, 0), cB + kstep, voffB); PG8_STAGE(PG8_SA(1, 0), cA + kstep, voffA); PG8_STAGE(PG8_SB(1, 1), cB + hstep + kstep, voffB);
;         PG8_WAIT_V(6); PG8_BAR;
.LBB0_1027:
	s_sext_i32_i16 s41, s22
	s_add_u32 s22, s26, 0xf1d8000
	s_addc_u32 s23, s27, 0
	v_readlane_b32 s10, v250, 30
	s_add_u32 s10, s26, s10
	v_readlane_b32 s11, v250, 29
	s_addc_u32 s11, s27, s11
	v_bfe_u32 v20, v16, 4, 2
	s_add_u32 s57, s10, 0x3a724000
	v_and_b32_e32 v17, 15, v16
	v_lshlrev_b32_e32 v18, 4, v20
	v_lshlrev_b32_e32 v16, 2, v16
	s_addc_u32 s62, s11, 0
	v_lshl_or_b32 v176, s34, 6, v17
	v_lshl_or_b32 v17, v17, 6, v18
	s_lshl_b32 s10, s34, 13
	v_and_b32_e32 v16, 32, v16
	v_bitop3_b32 v21, v17, s10, v16 bitop3:0xde
	s_lshl_b32 s10, s25, 5
	s_and_b32 s34, s10, 0x60
	s_add_i32 m0, s9, 0x18000
	v_lshl_add_u64 v[8:9], v[8:9], 0, s[28:29]
	s_lshl_b32 s10, s34, 7
	s_waitcnt vmcnt(2)
	s_barrier
	global_load_lds_dwordx4 v[8:9], off
	v_lshl_add_u64 v[6:7], v[6:7], 0, s[28:29]
	s_add_i32 m0, s9, 0x1a000
	s_add_i32 s63, s9, 0x8000
	s_add_i32 s64, s9, 0xa000
	v_bitop3_b32 v177, v17, s10, v16 bitop3:0xde
	global_load_lds_dwordx4 v[6:7], off
	v_lshl_add_u64 v[2:3], v[2:3], 0, s[28:29]
	s_mov_b32 m0, s63
	s_add_u32 s10, s50, 0x40080
	global_load_lds_dwordx4 v[2:3], off
	v_lshl_add_u64 v[2:3], v[4:5], 0, s[28:29]
	s_mov_b32 m0, s64
	s_addc_u32 s11, s51, 0
	global_load_lds_dwordx4 v[2:3], off
	s_add_i32 m0, s9, 0x1c000
	v_lshl_add_u64 v[2:3], s[10:11], 0, v[0:1]
	global_load_lds_dwordx4 v[2:3], off
	v_lshl_add_u64 v[2:3], s[10:11], 0, v[146:147]
	s_add_i32 m0, s9, 0x1e000
	v_mov_b32_e32 v19, v1
	global_load_lds_dwordx4 v[2:3], off
	v_lshl_add_u64 v[2:3], s[26:27], 0, v[18:19]
	s_mov_b64 s[10:11], 0x3acd0000
	v_lshl_add_u64 v[152:153], v[2:3], 0, s[10:11]
	v_lshlrev_b32_e32 v2, 14, v10
	v_and_b32_e32 v2, 0xffff8000, v2
	v_lshl_add_u32 v2, v11, 11, v2
	v_and_b32_e32 v3, 1, v10
	v_lshl_or_b32 v2, v3, 6, v2
	v_lshl_add_u32 v154, v12, 1, v2
	v_lshlrev_b32_e32 v2, 14, v14
	v_and_b32_e32 v2, 0xffff8000, v2
	s_waitcnt vmcnt(6)
	v_lshl_add_u32 v2, v13, 11, v2
	v_and_b32_e32 v3, 1, v14
	s_cmpk_lt_u32 s24, 0x100
	v_lshl_or_b32 v2, v3, 6, v2
	s_cselect_b64 s[24:25], -1, 0
	v_lshl_or_b32 v178, v20, 3, s34
	v_mov_b32_e32 v155, v1
	v_lshl_add_u32 v156, v15, 1, v2
	v_mov_b32_e32 v157, v1
	s_mov_b32 s65, 0
	v_add_u32_e32 v179, 16, v21
	v_lshlrev_b32_e32 v244, 4, v228
	v_readfirstlane_b32 s98, v163
	v_readfirstlane_b32 s100, v152
	v_readfirstlane_b32 s101, v153
	s_lshl_b32 s98, s98, 5
	s_lshl_b32 s99, s52, 6
	s_lshl_b32 s32, s40, 14
	s_add_i32 s99, s99, s32
	s_add_i32 s99, s99, s98
	s_add_u32 s100, s100, s99
	s_addc_u32 s101, s101, 0
	s_add_i32 m0, s98, 0x20010
	s_nop 0
	global_load_lds_dwordx4 v244, s[100:101]
	global_load_lds_dwordx4 v244, s[100:101] offset:1024
	s_lshl_b32 s99, s40, 8
	s_add_i32 s99, s99, s52
	s_min_i32 s99, s99, 0x10000
	s_ashr_i32 s99, s99, 13
	s_mulk_i32 s99, 0x1600
	s_lshl_b32 s99, s99, 2
	s_lshl_b32 s32, s41, 10
	s_add_i32 s99, s99, s32
	s_add_u32 s100, s57, s99
	s_addc_u32 s101, s62, 0
	s_mov_b32 m0, 0x24010
	s_nop 0
	global_load_lds_dwordx4 v244, s[100:101]
	s_barrier
	s_branch .LBB0_1030

; template <class Epi, class Sched, bool ALIGN_EPI = false, bool SP2 = false>
; __device__ __forceinline__ void gemm_phase(PG8_LAS unsigned char* lds, const Gemm g, const Sched& S, const Epi& E) {
;     ...
;         const bool has_next = S.next(ui + 1, nxt);
;         const char* nA = has_next ? (const char*)g.A + (size_t)nxt.pm * tstep : cA; const char* nB = has_next ? (const char*)g.Bt + (size_t)nxt.pn * tstep : cB;
;     ...
; #pragma unroll
;         for (int a = 0; a < 2; ++a)
; #pragma unroll
;             for (int b = 0; b < 2; ++b)
; #pragma unroll
;                 for (int m = 0; m < 4; ++m)
; #pragma unroll
;                     for (int n = 0; n < 2; ++n) acc[a][b][m][n] = (f32x4){0.f, 0.f, 0.f, 0.f};
;         cur = nxt; cA = nA; cB = nB; ++ui;
.LBB0_1032:
	s_and_b64 s[98:99], s[38:39], exec
	s_cselect_b32 s71, s42, s40
	s_cselect_b32 s73, s26, s41
	s_ashr_i32 s43, s42, 31
	s_lshl_b64 s[10:11], s[42:43], 19
	s_add_u32 s44, s2, s10
	s_addc_u32 s45, s3, s11
	s_and_b64 s[10:11], s[38:39], exec
	s_cselect_b32 s34, s45, s59
	s_cselect_b32 s35, s44, s58
	s_ashr_i32 s27, s26, 31
	s_lshl_b64 s[10:11], s[26:27], 19
	s_add_u32 s48, s4, s10
	s_addc_u32 s49, s5, s11
	s_and_b64 s[10:11], s[38:39], exec
	s_cselect_b32 s27, s49, s51
	s_cselect_b32 s43, s48, s50
	s_add_u32 s66, s50, 0x100
	s_addc_u32 s67, s51, 0
	s_add_u32 s50, s58, 0x40080
	v_mov_b32_e32 v2, 0
	s_addc_u32 s51, s59, 0
	s_mov_b32 s68, -2
	v_mov_b32_e32 v3, v2
	v_mov_b32_e32 v4, v2
	v_mov_b32_e32 v5, v2
	v_mov_b32_e32 v6, v2
	v_mov_b32_e32 v7, v2
	v_mov_b32_e32 v8, v2
	v_mov_b32_e32 v9, v2
	v_mov_b32_e32 v18, v2
	v_mov_b32_e32 v19, v2
	v_mov_b32_e32 v20, v2
	v_mov_b32_e32 v21, v2
	v_mov_b32_e32 v22, v2
	v_mov_b32_e32 v23, v2
	v_mov_b32_e32 v24, v2
	v_mov_b32_e32 v25, v2
	v_mov_b32_e32 v34, v2
	v_mov_b32_e32 v35, v2
	v_mov_b32_e32 v36, v2
	v_mov_b32_e32 v37, v2
	v_mov_b32_e32 v38, v2
	v_mov_b32_e32 v39, v2
	v_mov_b32_e32 v40, v2
	v_mov_b32_e32 v41, v2
	v_mov_b32_e32 v50, v2
	v_mov_b32_e32 v51, v2
	v_mov_b32_e32 v52, v2
	v_mov_b32_e32 v53, v2
	v_mov_b32_e32 v54, v2
	v_mov_b32_e32 v55, v2
	v_mov_b32_e32 v56, v2
	v_mov_b32_e32 v57, v2
	v_mov_b32_e32 v10, v2
	v_mov_b32_e32 v11, v2
	v_mov_b32_e32 v12, v2
	v_mov_b32_e32 v13, v2
	v_mov_b32_e32 v14, v2
	v_mov_b32_e32 v15, v2
	v_mov_b32_e32 v16, v2
	v_mov_b32_e32 v17, v2
	v_mov_b32_e32 v26, v2
	v_mov_b32_e32 v27, v2
	v_mov_b32_e32 v28, v2
	v_mov_b32_e32 v29, v2
	v_mov_b32_e32 v30, v2
	v_mov_b32_e32 v31, v2
	v_mov_b32_e32 v32, v2
	v_mov_b32_e32 v33, v2
	v_mov_b32_e32 v42, v2
	v_mov_b32_e32 v43, v2
	v_mov_b32_e32 v44, v2
	v_mov_b32_e32 v45, v2
	v_mov_b32_e32 v46, v2
	v_mov_b32_e32 v47, v2
	v_mov_b32_e32 v48, v2
	v_mov_b32_e32 v49, v2
	v_mov_b32_e32 v58, v2
	v_mov_b32_e32 v59, v2
	v_mov_b32_e32 v60, v2
	v_mov_b32_e32 v61, v2
	v_mov_b32_e32 v62, v2
	v_mov_b32_e32 v63, v2
	v_mov_b32_e32 v64, v2
	v_mov_b32_e32 v65, v2
	v_mov_b32_e32 v66, v2
	v_mov_b32_e32 v67, v2
	v_mov_b32_e32 v68, v2
	v_mov_b32_e32 v69, v2
	v_mov_b32_e32 v70, v2
	v_mov_b32_e32 v71, v2
	v_mov_b32_e32 v72, v2
	v_mov_b32_e32 v73, v2
	v_mov_b32_e32 v82, v2
	v_mov_b32_e32 v83, v2
	v_mov_b32_e32 v84, v2
	v_mov_b32_e32 v85, v2
	v_mov_b32_e32 v86, v2
	v_mov_b32_e32 v87, v2
	v_mov_b32_e32 v88, v2
	v_mov_b32_e32 v89, v2
	v_mov_b32_e32 v98, v2
	v_mov_b32_e32 v99, v2
	v_mov_b32_e32 v100, v2
	v_mov_b32_e32 v101, v2
	v_mov_b32_e32 v102, v2
	v_mov_b32_e32 v103, v2
	v_mov_b32_e32 v104, v2
	v_mov_b32_e32 v105, v2
	v_mov_b32_e32 v114, v2
	v_mov_b32_e32 v115, v2
	v_mov_b32_e32 v116, v2
	v_mov_b32_e32 v117, v2
	v_mov_b32_e32 v118, v2
	v_mov_b32_e32 v119, v2
	v_mov_b32_e32 v120, v2
	v_mov_b32_e32 v121, v2
	v_mov_b32_e32 v74, v2
	v_mov_b32_e32 v75, v2
	v_mov_b32_e32 v76, v2
	v_mov_b32_e32 v77, v2
	v_mov_b32_e32 v78, v2
	v_mov_b32_e32 v79, v2
	v_mov_b32_e32 v80, v2
	v_mov_b32_e32 v81, v2
	v_mov_b32_e32 v90, v2
	v_mov_b32_e32 v91, v2
	v_mov_b32_e32 v92, v2
	v_mov_b32_e32 v93, v2
	v_mov_b32_e32 v94, v2
	v_mov_b32_e32 v95, v2
	v_mov_b32_e32 v96, v2
	v_mov_b32_e32 v97, v2
	v_mov_b32_e32 v106, v2
	v_mov_b32_e32 v107, v2
	v_mov_b32_e32 v108, v2
	v_mov_b32_e32 v109, v2
	v_mov_b32_e32 v110, v2
	v_mov_b32_e32 v111, v2
	v_mov_b32_e32 v112, v2
	v_mov_b32_e32 v113, v2
	v_mov_b32_e32 v122, v2
	v_mov_b32_e32 v123, v2
	v_mov_b32_e32 v124, v2
	v_mov_b32_e32 v125, v2
	v_mov_b32_e32 v126, v2
	v_mov_b32_e32 v127, v2
	v_mov_b32_e32 v128, v2
	v_mov_b32_e32 v129, v2

; __device__ __forceinline__ unsigned pk2(float lo, float hi) { return pg8::cvt_pk_bf16(lo, hi); }
;     __device__ __forceinline__ void operator()(const f32x4 (&acc)[2][2][4][2], const pg8::Unit& u, int wr, int wc, int fr, int fq) const {
;         const int row0 = u.pm * 256 + wr * 64 + fr, col0 = u.pn * 256 + wc * 32 + 8 * fq;
;         const int Rt = rowbase + u.pm * 256;
;         const float* bp = bias + (size_t)(Rt < TL ? (Rt >> 13) : 8) * FF2 + col0;
;         f32x4 bv[2][2];
; #pragma unroll
;         for (int bj = 0; bj < 2; ++bj) { bv[bj][0] = *(const f32x4*)(bp + bj * 128); bv[bj][1] = *(const f32x4*)(bp + bj * 128 + 4); }
; #pragma unroll
;         for (int ai = 0; ai < 2; ++ai)
; #pragma unroll
;             for (int m = 0; m < 4; ++m) { const int r = row0 + ai * 128 + m * 16, Rg = rowbase + r;
;                 const f32x4 q = *(const f32x4*)(stat + (size_t)Rg * 16 + fq * 4);
;                 float ssq = (q[0] + q[1]) + (q[2] + q[3]); ssq += __shfl_xor(ssq, 16); ssq += __shfl_xor(ssq, 32);
;                 const float rstd = rsqrtf(ssq * (1.f / DM) + 1e-6f);
;                 bf16_t* rowp = O + (size_t)r * ldc + col0;
; #pragma unroll
;                 for (int bj = 0; bj < 2; ++bj) { const f32x4 v0 = acc[ai][bj][m][0] * rstd + bv[bj][0], v1 = acc[ai][bj][m][1] * rstd + bv[bj][1];
;                     u32x4 w; w.x = pk2(v0[0], v0[1]); w.y = pk2(v0[2], v0[3]); w.z = pk2(v1[0], v1[1]); w.w = pk2(v1[2], v1[3]);
;                     *(u32x4*)(rowp + bj * 128) = w; } }
.LBB0_1036:
	s_lshl_b32 s10, s40, 8
	v_add_u32_e32 v180, s10, v176
	v_add_u32_e32 v130, s52, v180
	v_ashrrev_i32_e32 v131, 31, v130
	v_lshlrev_b64 v[130:131], 6, v[130:131]
	v_lshl_add_u64 v[130:131], v[152:153], 0, v[130:131]
	v_lshlrev_b32_e32 v194, 6, v176
	v_and_b32_e32 v195, 48, v163
	v_add_u32_e32 v194, v194, v195
	v_add_u32_e32 v194, 0x20010, v194
	ds_read_b128 v[182:185], v194
	ds_read_b128 v[196:199], v194 offset:1024
	ds_read_b128 v[200:203], v194 offset:2048
	ds_read_b128 v[204:207], v194 offset:3072
	ds_read_b128 v[208:211], v194 offset:8192
	ds_read_b128 v[212:215], v194 offset:9216
	ds_read_b128 v[216:219], v194 offset:10240
	ds_read_b128 v[220:223], v194 offset:11264
	s_add_i32 s10, s10, s52
	s_min_i32 s10, s10, 0x10000
	s_ashr_i32 s10, s10, 13
	s_mulk_i32 s10, 0x1600
	s_ashr_i32 s11, s10, 31
	s_lshl_b64 s[10:11], s[10:11], 2
	v_lshl_or_b32 v160, s41, 8, v178
	s_add_u32 s10, s57, s10
	v_ashrrev_i32_e32 v161, 31, v160
	s_addc_u32 s11, s62, s11
	v_lshl_add_u64 v[130:131], v[160:161], 2, s[10:11]
	v_lshlrev_b32_e32 v195, 2, v178
	v_add_u32_e32 v195, 0x24010, v195
	ds_read_b128 v[142:145], v195
	ds_read_b128 v[138:141], v195 offset:16
	ds_read_b128 v[134:137], v195 offset:512
	ds_read_b128 v[130:133], v195 offset:528
	v_and_b32_e32 v186, 64, v228
	v_xor_b32_e32 v181, 16, v228
	v_add_u32_e32 v189, 64, v186
	v_cmp_lt_i32_e32 vcc, v181, v189
	v_xor_b32_e32 v188, 32, v228
	v_or_b32_e32 v192, 16, v180
	v_cndmask_b32_e32 v181, v228, v181, vcc
	v_lshlrev_b32_e32 v181, 2, v181
	v_cmp_lt_i32_e32 vcc, v188, v189
	v_mov_b64_e32 v[158:159], s[22:23]
	v_lshlrev_b64 v[160:161], 1, v[160:161]
	s_mov_b64 s[34:35], -1
	s_waitcnt vmcnt(0) lgkmcnt(0)
	s_barrier
	v_lshlrev_b32_e32 v244, 4, v228
	v_readfirstlane_b32 s98, v163
	v_readfirstlane_b32 s100, v152
	v_readfirstlane_b32 s101, v153
	s_lshl_b32 s98, s98, 5
	s_lshl_b32 s99, s52, 6
	s_lshl_b32 s32, s71, 14
	s_add_i32 s99, s99, s32
	s_add_i32 s99, s99, s98
	s_add_u32 s100, s100, s99
	s_addc_u32 s101, s101, 0
	s_add_i32 m0, s98, 0x20010
	s_nop 0
	global_load_lds_dwordx4 v244, s[100:101]
	global_load_lds_dwordx4 v244, s[100:101] offset:1024
	s_lshl_b32 s99, s71, 8
	s_add_i32 s99, s99, s52
	s_min_i32 s99, s99, 0x10000
	s_ashr_i32 s99, s99, 13
	s_mulk_i32 s99, 0x1600
	s_lshl_b32 s99, s99, 2
	s_lshl_b32 s32, s73, 10
	s_add_i32 s99, s99, s32
	s_add_u32 s100, s57, s99
	s_addc_u32 s101, s62, 0
	s_mov_b32 m0, 0x24010
	s_nop 0
	global_load_lds_dwordx4 v244, s[100:101]
	v_mov_b32_e32 v186, v183
	v_mov_b32_e32 v187, v184
	v_mov_b32_e32 v183, v185
	v_pk_add_f32 v[182:183], v[186:187], v[182:183]
	v_mad_i64_i32 v[184:185], s[10:11], v180, s92, v[158:159]
	v_add_f32_e32 v183, v182, v183
	ds_bpermute_b32 v186, v181, v183
	v_cndmask_b32_e32 v182, v228, v188, vcc
	v_lshlrev_b32_e32 v182, 2, v182
	v_lshl_add_u64 v[184:185], v[184:185], 0, v[160:161]
	s_waitcnt lgkmcnt(0)
	v_add_f32_e32 v183, v183, v186
	ds_bpermute_b32 v187, v182, v183
	v_add_u32_e32 v186, s52, v192
	s_waitcnt lgkmcnt(0)
	v_add_f32_e32 v183, v183, v187
	v_fmamk_f32 v183, v183, 0x3a800000, v162
	v_mul_f32_e32 v187, 0x4b800000, v183
	v_cmp_gt_f32_e32 vcc, s82, v183
	s_nop 1
	v_cndmask_b32_e32 v183, v183, v187, vcc
	v_rsq_f32_e32 v183, v183
	v_ashrrev_i32_e32 v187, 31, v186
	v_lshlrev_b64 v[186:187], 6, v[186:187]
	v_lshl_add_u64 v[186:187], v[152:153], 0, v[186:187]
	v_mul_f32_e32 v188, 0x45800000, v183
	v_cndmask_b32_e32 v188, v183, v188, vcc
	v_pk_fma_f32 v[128:129], v[128:129], v[188:189], v[144:145] op_sel_hi:[1,0,1]
	v_pk_fma_f32 v[126:127], v[126:127], v[188:189], v[142:143] op_sel_hi:[1,0,1]
	v_pk_fma_f32 v[124:125], v[124:125], v[188:189], v[140:141] op_sel_hi:[1,0,1]
	v_pk_fma_f32 v[122:123], v[122:123], v[188:189], v[138:139] op_sel_hi:[1,0,1]
	v_pk_fma_f32 v[120:121], v[120:121], v[188:189], v[136:137] op_sel_hi:[1,0,1]
	v_pk_fma_f32 v[118:119], v[118:119], v[188:189], v[134:135] op_sel_hi:[1,0,1]
	v_pk_fma_f32 v[190:191], v[116:117], v[188:189], v[132:133] op_sel_hi:[1,0,1]
	v_pk_fma_f32 v[188:189], v[114:115], v[188:189], v[130:131] op_sel_hi:[1,0,1]
	v_cvt_pk_bf16_f32 v114, v126, v127
	v_cvt_pk_bf16_f32 v115, v128, v129
	v_cvt_pk_bf16_f32 v116, v122, v123
	v_cvt_pk_bf16_f32 v117, v124, v125
	v_cvt_pk_bf16_f32 v118, v118, v119
	v_cvt_pk_bf16_f32 v119, v120, v121
	v_cvt_pk_bf16_f32 v120, v188, v189
	v_cvt_pk_bf16_f32 v121, v190, v191
	global_store_dwordx4 v[184:185], v[114:117], off
	global_store_dwordx4 v[184:185], v[118:121], off offset:256
	v_or_b32_e32 v122, 32, v180
	s_nop 1
	v_add_f32_e32 v114, v196, v197
	v_add_f32_e32 v115, v198, v199
	v_add_u32_e32 v116, s52, v122
	v_add_f32_e32 v114, v114, v115
	ds_bpermute_b32 v115, v181, v114
	s_waitcnt lgkmcnt(0)
	v_add_f32_e32 v117, v114, v115
	ds_bpermute_b32 v118, v182, v117
	v_mad_i64_i32 v[114:115], s[10:11], v192, s92, v[158:159]
	v_lshl_add_u64 v[114:115], v[114:115], 0, v[160:161]
	s_waitcnt lgkmcnt(0)
; __device__ __forceinline__ unsigned pk2(float lo, float hi) { return pg8::cvt_pk_bf16(lo, hi); }
;     __device__ __forceinline__ void operator()(const f32x4 (&acc)[2][2][4][2], const pg8::Unit& u, int wr, int wc, int fr, int fq) const {
;     ...
;             for (int m = 0; m < 4; ++m) { const int r = row0 + ai * 128 + m * 16, Rg = rowbase + r;
;                 const f32x4 q = *(const f32x4*)(stat + (size_t)Rg * 16 + fq * 4);
;                 float ssq = (q[0] + q[1]) + (q[2] + q[3]); ssq += __shfl_xor(ssq, 16); ssq += __shfl_xor(ssq, 32);
;                 const float rstd = rsqrtf(ssq * (1.f / DM) + 1e-6f);
;                 bf16_t* rowp = O + (size_t)r * ldc + col0;
; #pragma unroll
;                 for (int bj = 0; bj < 2; ++bj) { const f32x4 v0 = acc[ai][bj][m][0] * rstd + bv[bj][0], v1 = acc[ai][bj][m][1] * rstd + bv[bj][1];
;                     u32x4 w; w.x = pk2(v0[0], v0[1]); w.y = pk2(v0[2], v0[3]); w.z = pk2(v1[0], v1[1]); w.w = pk2(v1[2], v1[3]);
;                     *(u32x4*)(rowp + bj * 128) = w; } }
	v_add_f32_e32 v117, v117, v118
	v_fmamk_f32 v117, v117, 0x3a800000, v162
	v_mul_f32_e32 v118, 0x4b800000, v117
	v_cmp_gt_f32_e32 vcc, s82, v117
	s_nop 1
	v_cndmask_b32_e32 v117, v117, v118, vcc
	v_rsq_f32_e32 v118, v117
	v_ashrrev_i32_e32 v117, 31, v116
	v_lshlrev_b64 v[116:117], 6, v[116:117]
	v_lshl_add_u64 v[116:117], v[152:153], 0, v[116:117]
	v_mul_f32_e32 v119, 0x45800000, v118
	v_cndmask_b32_e32 v118, v118, v119, vcc
	v_pk_fma_f32 v[112:113], v[112:113], v[118:119], v[144:145] op_sel_hi:[1,0,1]
	v_pk_fma_f32 v[110:111], v[110:111], v[118:119], v[142:143] op_sel_hi:[1,0,1]
	v_pk_fma_f32 v[108:109], v[108:109], v[118:119], v[140:141] op_sel_hi:[1,0,1]
	v_pk_fma_f32 v[106:107], v[106:107], v[118:119], v[138:139] op_sel_hi:[1,0,1]
	v_pk_fma_f32 v[104:105], v[104:105], v[118:119], v[136:137] op_sel_hi:[1,0,1]
	v_pk_fma_f32 v[102:103], v[102:103], v[118:119], v[134:135] op_sel_hi:[1,0,1]
	v_pk_fma_f32 v[120:121], v[100:101], v[118:119], v[132:133] op_sel_hi:[1,0,1]
	v_pk_fma_f32 v[118:119], v[98:99], v[118:119], v[130:131] op_sel_hi:[1,0,1]
	v_cvt_pk_bf16_f32 v98, v110, v111
	v_cvt_pk_bf16_f32 v99, v112, v113
	v_cvt_pk_bf16_f32 v100, v106, v107
	v_cvt_pk_bf16_f32 v101, v108, v109
	v_cvt_pk_bf16_f32 v102, v102, v103
	v_cvt_pk_bf16_f32 v103, v104, v105
	v_cvt_pk_bf16_f32 v104, v118, v119
	v_cvt_pk_bf16_f32 v105, v120, v121
	global_store_dwordx4 v[114:115], v[98:101], off
	global_store_dwordx4 v[114:115], v[102:105], off offset:256
	v_or_b32_e32 v106, 48, v180
	s_nop 1
	v_add_f32_e32 v98, v200, v201
	v_add_f32_e32 v99, v202, v203
	v_add_u32_e32 v100, s52, v106
	v_add_f32_e32 v98, v98, v99
	ds_bpermute_b32 v99, v181, v98
	s_waitcnt lgkmcnt(0)
	v_add_f32_e32 v101, v98, v99
	ds_bpermute_b32 v102, v182, v101
	v_mad_i64_i32 v[98:99], s[10:11], v122, s92, v[158:159]
	v_lshl_add_u64 v[98:99], v[98:99], 0, v[160:161]
	s_waitcnt lgkmcnt(0)
	v_add_f32_e32 v101, v101, v102
	v_fmamk_f32 v101, v101, 0x3a800000, v162
	v_mul_f32_e32 v102, 0x4b800000, v101
	v_cmp_gt_f32_e32 vcc, s82, v101
	s_nop 1
	v_cndmask_b32_e32 v101, v101, v102, vcc
	v_rsq_f32_e32 v102, v101
	v_ashrrev_i32_e32 v101, 31, v100
	v_lshlrev_b64 v[100:101], 6, v[100:101]
	v_lshl_add_u64 v[100:101], v[152:153], 0, v[100:101]
	v_mul_f32_e32 v103, 0x45800000, v102
	v_cndmask_b32_e32 v102, v102, v103, vcc
	v_pk_fma_f32 v[96:97], v[96:97], v[102:103], v[144:145] op_sel_hi:[1,0,1]
	v_pk_fma_f32 v[94:95], v[94:95], v[102:103], v[142:143] op_sel_hi:[1,0,1]
	v_pk_fma_f32 v[92:93], v[92:93], v[102:103], v[140:141] op_sel_hi:[1,0,1]
	v_pk_fma_f32 v[90:91], v[90:91], v[102:103], v[138:139] op_sel_hi:[1,0,1]
	v_pk_fma_f32 v[88:89], v[88:89], v[102:103], v[136:137] op_sel_hi:[1,0,1]
	v_pk_fma_f32 v[86:87], v[86:87], v[102:103], v[134:135] op_sel_hi:[1,0,1]
	v_pk_fma_f32 v[104:105], v[84:85], v[102:103], v[132:133] op_sel_hi:[1,0,1]
	v_pk_fma_f32 v[102:103], v[82:83], v[102:103], v[130:131] op_sel_hi:[1,0,1]
	v_cvt_pk_bf16_f32 v82, v94, v95
	v_cvt_pk_bf16_f32 v83, v96, v97
	v_cvt_pk_bf16_f32 v84, v90, v91
	v_cvt_pk_bf16_f32 v85, v92, v93
	v_cvt_pk_bf16_f32 v86, v86, v87
	v_cvt_pk_bf16_f32 v87, v88, v89
	v_cvt_pk_bf16_f32 v88, v102, v103
	v_cvt_pk_bf16_f32 v89, v104, v105
	global_store_dwordx4 v[98:99], v[82:85], off
	global_store_dwordx4 v[98:99], v[86:89], off offset:256
	v_add_u32_e32 v90, 0x80, v180
	s_nop 1
	v_add_f32_e32 v82, v204, v205
	v_add_f32_e32 v83, v206, v207
	v_add_u32_e32 v84, s52, v90
	v_add_f32_e32 v82, v82, v83
	ds_bpermute_b32 v83, v181, v82
	s_waitcnt lgkmcnt(0)
	v_add_f32_e32 v85, v82, v83
	ds_bpermute_b32 v86, v182, v85
	v_mad_i64_i32 v[82:83], s[10:11], v106, s92, v[158:159]
	v_lshl_add_u64 v[82:83], v[82:83], 0, v[160:161]
	s_waitcnt lgkmcnt(0)
	v_add_f32_e32 v85, v85, v86
	v_fmamk_f32 v85, v85, 0x3a800000, v162
	v_mul_f32_e32 v86, 0x4b800000, v85
	v_cmp_gt_f32_e32 vcc, s82, v85
	s_nop 1
	v_cndmask_b32_e32 v85, v85, v86, vcc
	v_rsq_f32_e32 v86, v85
	v_ashrrev_i32_e32 v85, 31, v84
	v_lshlrev_b64 v[84:85], 6, v[84:85]
	v_lshl_add_u64 v[84:85], v[152:153], 0, v[84:85]
	v_mul_f32_e32 v87, 0x45800000, v86
	v_cndmask_b32_e32 v86, v86, v87, vcc
	v_pk_fma_f32 v[80:81], v[80:81], v[86:87], v[144:145] op_sel_hi:[1,0,1]
	v_pk_fma_f32 v[78:79], v[78:79], v[86:87], v[142:143] op_sel_hi:[1,0,1]
	v_pk_fma_f32 v[76:77], v[76:77], v[86:87], v[140:141] op_sel_hi:[1,0,1]
	v_pk_fma_f32 v[74:75], v[74:75], v[86:87], v[138:139] op_sel_hi:[1,0,1]
	v_pk_fma_f32 v[72:73], v[72:73], v[86:87], v[136:137] op_sel_hi:[1,0,1]
	v_pk_fma_f32 v[70:71], v[70:71], v[86:87], v[134:135] op_sel_hi:[1,0,1]
	v_pk_fma_f32 v[88:89], v[68:69], v[86:87], v[132:133] op_sel_hi:[1,0,1]
	v_pk_fma_f32 v[86:87], v[66:67], v[86:87], v[130:131] op_sel_hi:[1,0,1]
	v_cvt_pk_bf16_f32 v66, v78, v79
	v_cvt_pk_bf16_f32 v67, v80, v81
	v_cvt_pk_bf16_f32 v68, v74, v75
	v_cvt_pk_bf16_f32 v69, v76, v77
	v_cvt_pk_bf16_f32 v70, v70, v71
	v_cvt_pk_bf16_f32 v71, v72, v73
	v_cvt_pk_bf16_f32 v72, v86, v87
	v_cvt_pk_bf16_f32 v73, v88, v89
	global_store_dwordx4 v[82:83], v[66:69], off
	global_store_dwordx4 v[82:83], v[70:73], off offset:256
	v_add_u32_e32 v74, 0x90, v180
	s_nop 1
	v_add_f32_e32 v66, v208, v209
	v_add_f32_e32 v67, v210, v211
	v_add_u32_e32 v68, s52, v74
	v_add_f32_e32 v66, v66, v67
	ds_bpermute_b32 v67, v181, v66
	s_waitcnt lgkmcnt(0)
	v_add_f32_e32 v69, v66, v67
	ds_bpermute_b32 v70, v182, v69
	v_mad_i64_i32 v[66:67], s[10:11], v90, s92, v[158:159]
	v_lshl_add_u64 v[66:67], v[66:67], 0, v[160:161]
	s_waitcnt lgkmcnt(0)
; __device__ __forceinline__ unsigned pk2(float lo, float hi) { return pg8::cvt_pk_bf16(lo, hi); }
;     __device__ __forceinline__ void operator()(const f32x4 (&acc)[2][2][4][2], const pg8::Unit& u, int wr, int wc, int fr, int fq) const {
;     ...
;             for (int m = 0; m < 4; ++m) { const int r = row0 + ai * 128 + m * 16, Rg = rowbase + r;
;                 const f32x4 q = *(const f32x4*)(stat + (size_t)Rg * 16 + fq * 4);
;                 float ssq = (q[0] + q[1]) + (q[2] + q[3]); ssq += __shfl_xor(ssq, 16); ssq += __shfl_xor(ssq, 32);
;                 const float rstd = rsqrtf(ssq * (1.f / DM) + 1e-6f);
;                 bf16_t* rowp = O + (size_t)r * ldc + col0;
; #pragma unroll
;                 for (int bj = 0; bj < 2; ++bj) { const f32x4 v0 = acc[ai][bj][m][0] * rstd + bv[bj][0], v1 = acc[ai][bj][m][1] * rstd + bv[bj][1];
;                     u32x4 w; w.x = pk2(v0[0], v0[1]); w.y = pk2(v0[2], v0[3]); w.z = pk2(v1[0], v1[1]); w.w = pk2(v1[2], v1[3]);
;                     *(u32x4*)(rowp + bj * 128) = w; } }
	v_add_f32_e32 v69, v69, v70
	v_fmamk_f32 v69, v69, 0x3a800000, v162
	v_mul_f32_e32 v70, 0x4b800000, v69
	v_cmp_gt_f32_e32 vcc, s82, v69
	s_nop 1
	v_cndmask_b32_e32 v69, v69, v70, vcc
	v_rsq_f32_e32 v70, v69
	v_ashrrev_i32_e32 v69, 31, v68
	v_lshlrev_b64 v[68:69], 6, v[68:69]
	v_lshl_add_u64 v[68:69], v[152:153], 0, v[68:69]
	v_mul_f32_e32 v71, 0x45800000, v70
	v_cndmask_b32_e32 v70, v70, v71, vcc
	v_pk_fma_f32 v[64:65], v[64:65], v[70:71], v[144:145] op_sel_hi:[1,0,1]
	v_pk_fma_f32 v[62:63], v[62:63], v[70:71], v[142:143] op_sel_hi:[1,0,1]
	v_pk_fma_f32 v[60:61], v[60:61], v[70:71], v[140:141] op_sel_hi:[1,0,1]
	v_pk_fma_f32 v[58:59], v[58:59], v[70:71], v[138:139] op_sel_hi:[1,0,1]
	v_pk_fma_f32 v[56:57], v[56:57], v[70:71], v[136:137] op_sel_hi:[1,0,1]
	v_pk_fma_f32 v[54:55], v[54:55], v[70:71], v[134:135] op_sel_hi:[1,0,1]
	v_pk_fma_f32 v[72:73], v[52:53], v[70:71], v[132:133] op_sel_hi:[1,0,1]
	v_pk_fma_f32 v[70:71], v[50:51], v[70:71], v[130:131] op_sel_hi:[1,0,1]
	v_cvt_pk_bf16_f32 v50, v62, v63
	v_cvt_pk_bf16_f32 v51, v64, v65
	v_cvt_pk_bf16_f32 v52, v58, v59
	v_cvt_pk_bf16_f32 v53, v60, v61
	v_cvt_pk_bf16_f32 v54, v54, v55
	v_cvt_pk_bf16_f32 v55, v56, v57
	v_cvt_pk_bf16_f32 v56, v70, v71
	v_cvt_pk_bf16_f32 v57, v72, v73
	global_store_dwordx4 v[66:67], v[50:53], off
	global_store_dwordx4 v[66:67], v[54:57], off offset:256
	v_add_u32_e32 v58, 0xa0, v180
	s_nop 1
	v_add_f32_e32 v50, v212, v213
	v_add_f32_e32 v51, v214, v215
	v_add_u32_e32 v52, s52, v58
	v_add_f32_e32 v50, v50, v51
	ds_bpermute_b32 v51, v181, v50
	s_waitcnt lgkmcnt(0)
	v_add_f32_e32 v53, v50, v51
	ds_bpermute_b32 v54, v182, v53
	v_mad_i64_i32 v[50:51], s[10:11], v74, s92, v[158:159]
	v_lshl_add_u64 v[50:51], v[50:51], 0, v[160:161]
	s_waitcnt lgkmcnt(0)
	v_add_f32_e32 v53, v53, v54
	v_fmamk_f32 v53, v53, 0x3a800000, v162
	v_mul_f32_e32 v54, 0x4b800000, v53
	v_cmp_gt_f32_e32 vcc, s82, v53
	s_nop 1
	v_cndmask_b32_e32 v53, v53, v54, vcc
	v_rsq_f32_e32 v54, v53
	v_ashrrev_i32_e32 v53, 31, v52
	v_lshlrev_b64 v[52:53], 6, v[52:53]
	v_lshl_add_u64 v[52:53], v[152:153], 0, v[52:53]
	v_mul_f32_e32 v55, 0x45800000, v54
	v_cndmask_b32_e32 v54, v54, v55, vcc
	v_pk_fma_f32 v[48:49], v[48:49], v[54:55], v[144:145] op_sel_hi:[1,0,1]
	v_pk_fma_f32 v[46:47], v[46:47], v[54:55], v[142:143] op_sel_hi:[1,0,1]
	v_pk_fma_f32 v[44:45], v[44:45], v[54:55], v[140:141] op_sel_hi:[1,0,1]
	v_pk_fma_f32 v[42:43], v[42:43], v[54:55], v[138:139] op_sel_hi:[1,0,1]
	v_pk_fma_f32 v[40:41], v[40:41], v[54:55], v[136:137] op_sel_hi:[1,0,1]
	v_pk_fma_f32 v[38:39], v[38:39], v[54:55], v[134:135] op_sel_hi:[1,0,1]
	v_pk_fma_f32 v[56:57], v[36:37], v[54:55], v[132:133] op_sel_hi:[1,0,1]
	v_pk_fma_f32 v[54:55], v[34:35], v[54:55], v[130:131] op_sel_hi:[1,0,1]
	v_cvt_pk_bf16_f32 v34, v46, v47
	v_cvt_pk_bf16_f32 v35, v48, v49
	v_cvt_pk_bf16_f32 v36, v42, v43
	v_cvt_pk_bf16_f32 v37, v44, v45
	v_cvt_pk_bf16_f32 v38, v38, v39
	v_cvt_pk_bf16_f32 v39, v40, v41
	v_cvt_pk_bf16_f32 v40, v54, v55
	v_cvt_pk_bf16_f32 v41, v56, v57
	global_store_dwordx4 v[50:51], v[34:37], off
	global_store_dwordx4 v[50:51], v[38:41], off offset:256
	v_add_u32_e32 v42, 0xb0, v180
	s_nop 1
	v_add_f32_e32 v34, v216, v217
	v_add_f32_e32 v35, v218, v219
	v_add_u32_e32 v36, s52, v42
	v_add_f32_e32 v34, v34, v35
	ds_bpermute_b32 v35, v181, v34
	s_waitcnt lgkmcnt(0)
	v_add_f32_e32 v37, v34, v35
	ds_bpermute_b32 v38, v182, v37
	v_mad_i64_i32 v[34:35], s[10:11], v58, s92, v[158:159]
	v_lshl_add_u64 v[34:35], v[34:35], 0, v[160:161]
	s_waitcnt lgkmcnt(0)
	v_add_f32_e32 v37, v37, v38
	v_fmamk_f32 v37, v37, 0x3a800000, v162
	v_mul_f32_e32 v38, 0x4b800000, v37
	v_cmp_gt_f32_e32 vcc, s82, v37
	s_nop 1
	v_cndmask_b32_e32 v37, v37, v38, vcc
	v_rsq_f32_e32 v38, v37
	v_ashrrev_i32_e32 v37, 31, v36
	v_lshlrev_b64 v[36:37], 6, v[36:37]
	v_lshl_add_u64 v[36:37], v[152:153], 0, v[36:37]
	v_mul_f32_e32 v39, 0x45800000, v38
	v_cndmask_b32_e32 v38, v38, v39, vcc
	v_pk_fma_f32 v[32:33], v[32:33], v[38:39], v[144:145] op_sel_hi:[1,0,1]
	v_pk_fma_f32 v[30:31], v[30:31], v[38:39], v[142:143] op_sel_hi:[1,0,1]
	v_pk_fma_f32 v[28:29], v[28:29], v[38:39], v[140:141] op_sel_hi:[1,0,1]
	v_pk_fma_f32 v[26:27], v[26:27], v[38:39], v[138:139] op_sel_hi:[1,0,1]
	v_pk_fma_f32 v[24:25], v[24:25], v[38:39], v[136:137] op_sel_hi:[1,0,1]
	v_pk_fma_f32 v[22:23], v[22:23], v[38:39], v[134:135] op_sel_hi:[1,0,1]
	v_pk_fma_f32 v[40:41], v[20:21], v[38:39], v[132:133] op_sel_hi:[1,0,1]
	v_pk_fma_f32 v[38:39], v[18:19], v[38:39], v[130:131] op_sel_hi:[1,0,1]
	v_cvt_pk_bf16_f32 v18, v30, v31
	v_cvt_pk_bf16_f32 v19, v32, v33
	v_cvt_pk_bf16_f32 v20, v26, v27
	v_cvt_pk_bf16_f32 v21, v28, v29
	v_cvt_pk_bf16_f32 v22, v22, v23
	v_cvt_pk_bf16_f32 v23, v24, v25
	v_cvt_pk_bf16_f32 v24, v38, v39
	v_cvt_pk_bf16_f32 v25, v40, v41
	global_store_dwordx4 v[34:35], v[18:21], off
	global_store_dwordx4 v[34:35], v[22:25], off offset:256
	s_andn2_b64 vcc, exec, s[38:39]
	s_nop 1
	v_add_f32_e32 v18, v220, v221
	v_add_f32_e32 v19, v222, v223
	s_nop 0
	v_add_f32_e32 v18, v18, v19
	ds_bpermute_b32 v19, v181, v18
	s_waitcnt lgkmcnt(0)
	v_add_f32_e32 v18, v18, v19
	ds_bpermute_b32 v19, v182, v18
	s_waitcnt lgkmcnt(0)
	v_add_f32_e32 v18, v18, v19
	v_fmamk_f32 v18, v18, 0x3a800000, v162
	v_mul_f32_e32 v19, 0x4b800000, v18
	v_cmp_gt_f32_e64 s[40:41], s82, v18
	s_nop 1
	v_cndmask_b32_e64 v18, v18, v19, s[40:41]
	v_rsq_f32_e32 v20, v18
	v_mad_i64_i32 v[18:19], s[10:11], v42, s92, v[158:159]
	v_lshl_add_u64 v[18:19], v[18:19], 0, v[160:161]
	v_mul_f32_e32 v21, 0x45800000, v20
	v_cndmask_b32_e64 v20, v20, v21, s[40:41]
	v_pk_fma_f32 v[16:17], v[16:17], v[20:21], v[144:145] op_sel_hi:[1,0,1]
	v_pk_fma_f32 v[14:15], v[14:15], v[20:21], v[142:143] op_sel_hi:[1,0,1]
	v_pk_fma_f32 v[12:13], v[12:13], v[20:21], v[140:141] op_sel_hi:[1,0,1]
	v_pk_fma_f32 v[10:11], v[10:11], v[20:21], v[138:139] op_sel_hi:[1,0,1]
	v_pk_fma_f32 v[8:9], v[8:9], v[20:21], v[136:137] op_sel_hi:[1,0,1]
	v_pk_fma_f32 v[6:7], v[6:7], v[20:21], v[134:135] op_sel_hi:[1,0,1]
	v_pk_fma_f32 v[22:23], v[4:5], v[20:21], v[132:133] op_sel_hi:[1,0,1]
	v_pk_fma_f32 v[20:21], v[2:3], v[20:21], v[130:131] op_sel_hi:[1,0,1]
	v_cvt_pk_bf16_f32 v2, v14, v15
	v_cvt_pk_bf16_f32 v3, v16, v17
	v_cvt_pk_bf16_f32 v4, v10, v11
	v_cvt_pk_bf16_f32 v5, v12, v13
	v_cvt_pk_bf16_f32 v6, v6, v7
	v_cvt_pk_bf16_f32 v7, v8, v9
	v_cvt_pk_bf16_f32 v8, v20, v21
	v_cvt_pk_bf16_f32 v9, v22, v23
	global_store_dwordx4 v[18:19], v[2:5], off
	global_store_dwordx4 v[18:19], v[6:9], off offset:256
	s_cbranch_vccnz .LBB0_1029
	s_andn2_b64 vcc, exec, s[20:21]
	s_cbranch_vccnz .LBB0_1028
	s_barrier
	s_branch .LBB0_1028

; #define PG8_STAGE(bufoff, gbase, voff) do { _Pragma("unroll") for (int _i = 0; _i < 2; ++_i) \
;         __builtin_amdgcn_global_load_lds((const unsigned*)((const char*)(gbase) + (voff)[_i]), (PG8_LAS unsigned*)(lds + (bufoff) + ldsw + _i * 8192), 16, 0, 0); } while (0)
; #define PG8_WAIT_V(n) asm volatile("s_waitcnt vmcnt(" #n ")" ::: "memory")
; #define PG8_BAR __builtin_amdgcn_s_barrier()
; template <class Epi, class Sched, bool ALIGN_EPI = false, bool SP2 = false>
; __device__ __forceinline__ void gemm_phase(PG8_LAS unsigned char* lds, const Gemm g, const Sched& S, const Epi& E) {
;     ...
;     for (int i = 0; i < 2; ++i) { int R, C; stage_rc(tid * 16 + i * 8192, R, C); const int Rb = Epi::PERM ? ((R & ~31) + perm32(R & 31)) : R;
;         voffA[i] = (unsigned)(R * K + C) * 2u; voffB[i] = (unsigned)(Rb * K + C) * 2u; }
;     const size_t kstep = (size_t)(BK * 2);
;     const size_t hstep = (size_t)HALF * K * 2;
;     const size_t tstep = 2 * hstep;
;     const unsigned ldsw = (unsigned)wid * 1024u;
;     const int aoff = lds_byte(wr * 64 + fr, fq * 8), boff = lds_byte(wc * 32 + fr, fq * 8);
;     ...
;         PG8_STAGE(PG8_SB(1, 0), cB + kstep, voffB); PG8_STAGE(PG8_SA(1, 0), cA + kstep, voffA); PG8_STAGE(PG8_SB(1, 1), cB + hstep + kstep, voffB);
;         PG8_WAIT_V(6); PG8_BAR;
.LBB0_1269:
	s_add_u32 s22, s50, 0xf1d8000
	v_readlane_b32 s8, v250, 38
	s_addc_u32 s23, s51, 0
	s_mul_i32 s8, s8, 0x63000
	s_add_u32 s8, s50, s8
	v_readlane_b32 s9, v250, 37
	s_addc_u32 s9, s51, s9
	v_bfe_u32 v20, v16, 4, 2
	s_add_u32 s8, s8, 0x3a724000
	v_and_b32_e32 v17, 15, v16
	v_lshlrev_b32_e32 v18, 4, v20
	v_lshlrev_b32_e32 v16, 2, v16
	s_addc_u32 s9, s9, 0
	v_lshl_or_b32 v178, s26, 6, v17
	v_lshl_or_b32 v17, v17, 6, v18
	s_lshl_b32 s10, s26, 13
	v_and_b32_e32 v16, 32, v16
	v_bitop3_b32 v21, v17, s10, v16 bitop3:0xde
	s_lshl_b32 s10, s25, 5
	s_and_b32 s26, s10, 0x60
	s_add_i32 m0, s4, 0x18000
	v_lshl_add_u64 v[8:9], v[8:9], 0, s[28:29]
	s_lshl_b32 s10, s26, 7
	s_waitcnt vmcnt(2)
	s_barrier
	global_load_lds_dwordx4 v[8:9], off
	v_lshl_add_u64 v[6:7], v[6:7], 0, s[28:29]
	s_add_i32 m0, s4, 0x1a000
	s_add_i32 s54, s4, 0x8000
	s_add_i32 s55, s4, 0xa000
	v_bitop3_b32 v179, v17, s10, v16 bitop3:0xde
	global_load_lds_dwordx4 v[6:7], off
	v_lshl_add_u64 v[2:3], v[2:3], 0, s[28:29]
	s_mov_b32 m0, s54
	s_add_u32 s10, s40, 0x40080
	global_load_lds_dwordx4 v[2:3], off
	v_lshl_add_u64 v[2:3], v[4:5], 0, s[28:29]
	s_mov_b32 m0, s55
	s_addc_u32 s11, s41, 0
	global_load_lds_dwordx4 v[2:3], off
	s_add_i32 m0, s4, 0x1c000
	v_lshl_add_u64 v[2:3], s[10:11], 0, v[0:1]
	global_load_lds_dwordx4 v[2:3], off
	v_lshl_add_u64 v[2:3], s[10:11], 0, v[146:147]
	s_add_i32 m0, s4, 0x1e000
	s_cmpk_lt_u32 s24, 0x100
	global_load_lds_dwordx4 v[2:3], off
	v_lshlrev_b32_e32 v2, 14, v10
	v_and_b32_e32 v2, 0xffff8000, v2
	v_lshl_add_u32 v2, v11, 11, v2
	v_and_b32_e32 v3, 1, v10
	v_lshl_or_b32 v2, v3, 6, v2
	v_lshl_add_u32 v154, v12, 1, v2
	v_lshlrev_b32_e32 v2, 14, v14
	v_and_b32_e32 v2, 0xffff8000, v2
	s_waitcnt vmcnt(6)
	v_lshl_add_u32 v2, v13, 11, v2
	v_and_b32_e32 v3, 1, v14
	v_mov_b32_e32 v19, v1
	v_lshl_or_b32 v2, v3, 6, v2
	v_readlane_b32 s10, v251, 61
	s_cselect_b64 s[24:25], -1, 0
	v_lshl_add_u64 v[152:153], s[62:63], 0, v[18:19]
	v_lshl_or_b32 v180, v20, 3, s26
	v_mov_b32_e32 v155, v1
	v_lshl_add_u32 v156, v15, 1, v2
	v_mov_b32_e32 v157, v1
	s_mov_b32 s56, 0
	v_add_u32_e32 v181, 16, v21
	v_readlane_b32 s57, v251, 53
	s_mov_b32 s58, s10
	v_lshlrev_b32_e32 v244, 4, v228
	v_readfirstlane_b32 s98, v163
	v_readfirstlane_b32 s100, v152
	v_readfirstlane_b32 s101, v153
	s_lshl_b32 s98, s98, 5
	s_lshl_b32 s99, 0, 6
	s_lshl_b32 s32, s58, 14
	s_add_i32 s99, s99, s32
	s_add_i32 s99, s99, s98
	s_add_u32 s100, s100, s99
	s_addc_u32 s101, s101, 0
	s_add_i32 m0, s98, 0x20010
	s_nop 0
	global_load_lds_dwordx4 v244, s[100:101]
	global_load_lds_dwordx4 v244, s[100:101] offset:1024
	s_lshl_b32 s99, s58, 8
	s_add_i32 s99, s99, 0
	s_min_i32 s99, s99, 0x10000
	s_ashr_i32 s99, s99, 13
	s_mulk_i32 s99, 0x1600
	s_lshl_b32 s99, s99, 2
	s_lshl_b32 s32, s57, 10
	s_add_i32 s99, s99, s32
	s_add_u32 s100, s8, s99
	s_addc_u32 s101, s9, 0
	s_mov_b32 m0, 0x24010
	s_nop 0
	global_load_lds_dwordx4 v244, s[100:101]
	s_barrier
	v_readlane_b32 s11, v251, 62
	s_branch .LBB0_1272

; template <class Epi, class Sched, bool ALIGN_EPI = false, bool SP2 = false>
; __device__ __forceinline__ void gemm_phase(PG8_LAS unsigned char* lds, const Gemm g, const Sched& S, const Epi& E) {
;     ...
;         const bool has_next = S.next(ui + 1, nxt);
;         const char* nA = has_next ? (const char*)g.A + (size_t)nxt.pm * tstep : cA; const char* nB = has_next ? (const char*)g.Bt + (size_t)nxt.pn * tstep : cB;
;     ...
; #pragma unroll
;         for (int a = 0; a < 2; ++a)
; #pragma unroll
;             for (int b = 0; b < 2; ++b)
; #pragma unroll
;                 for (int m = 0; m < 4; ++m)
; #pragma unroll
;                     for (int n = 0; n < 2; ++n) acc[a][b][m][n] = (f32x4){0.f, 0.f, 0.f, 0.f};
;         cur = nxt; cA = nA; cB = nB; ++ui;
.LBB0_1274:
	s_and_b64 s[98:99], s[38:39], exec
	s_cselect_b32 s71, s42, s58
	s_cselect_b32 s72, s26, s57
	s_ashr_i32 s43, s42, 31
	s_lshl_b64 s[10:11], s[42:43], 19
	s_add_u32 s44, s60, s10
	s_addc_u32 s45, s61, s11
	s_and_b64 s[10:11], s[38:39], exec
	s_cselect_b32 s34, s45, s49
	s_cselect_b32 s35, s44, s48
	s_ashr_i32 s27, s26, 31
	s_lshl_b64 s[10:11], s[26:27], 19
	s_add_u32 s46, s0, s10
	s_addc_u32 s47, s2, s11
	s_and_b64 s[10:11], s[38:39], exec
	s_cselect_b32 s27, s47, s41
	s_cselect_b32 s43, s46, s40
	s_add_u32 s59, s40, 0x100
	s_addc_u32 s62, s41, 0
	s_add_u32 s40, s48, 0x40080
	v_mov_b32_e32 v2, 0
	s_addc_u32 s41, s49, 0
	s_mov_b32 s63, -2
	v_mov_b32_e32 v3, v2
	v_mov_b32_e32 v4, v2
	v_mov_b32_e32 v5, v2
	v_mov_b32_e32 v6, v2
	v_mov_b32_e32 v7, v2
	v_mov_b32_e32 v8, v2
	v_mov_b32_e32 v9, v2
	v_mov_b32_e32 v18, v2
	v_mov_b32_e32 v19, v2
	v_mov_b32_e32 v20, v2
	v_mov_b32_e32 v21, v2
	v_mov_b32_e32 v22, v2
	v_mov_b32_e32 v23, v2
	v_mov_b32_e32 v24, v2
	v_mov_b32_e32 v25, v2
	v_mov_b32_e32 v34, v2
	v_mov_b32_e32 v35, v2
	v_mov_b32_e32 v36, v2
	v_mov_b32_e32 v37, v2
	v_mov_b32_e32 v38, v2
	v_mov_b32_e32 v39, v2
	v_mov_b32_e32 v40, v2
	v_mov_b32_e32 v41, v2
	v_mov_b32_e32 v50, v2
	v_mov_b32_e32 v51, v2
	v_mov_b32_e32 v52, v2
	v_mov_b32_e32 v53, v2
	v_mov_b32_e32 v54, v2
	v_mov_b32_e32 v55, v2
	v_mov_b32_e32 v56, v2
	v_mov_b32_e32 v57, v2
	v_mov_b32_e32 v10, v2
	v_mov_b32_e32 v11, v2
	v_mov_b32_e32 v12, v2
	v_mov_b32_e32 v13, v2
	v_mov_b32_e32 v14, v2
	v_mov_b32_e32 v15, v2
	v_mov_b32_e32 v16, v2
	v_mov_b32_e32 v17, v2
	v_mov_b32_e32 v26, v2
	v_mov_b32_e32 v27, v2
	v_mov_b32_e32 v28, v2
	v_mov_b32_e32 v29, v2
	v_mov_b32_e32 v30, v2
	v_mov_b32_e32 v31, v2
	v_mov_b32_e32 v32, v2
	v_mov_b32_e32 v33, v2
	v_mov_b32_e32 v42, v2
	v_mov_b32_e32 v43, v2
	v_mov_b32_e32 v44, v2
	v_mov_b32_e32 v45, v2
	v_mov_b32_e32 v46, v2
	v_mov_b32_e32 v47, v2
	v_mov_b32_e32 v48, v2
	v_mov_b32_e32 v49, v2
	v_mov_b32_e32 v58, v2
	v_mov_b32_e32 v59, v2
	v_mov_b32_e32 v60, v2
	v_mov_b32_e32 v61, v2
	v_mov_b32_e32 v62, v2
	v_mov_b32_e32 v63, v2
	v_mov_b32_e32 v64, v2
	v_mov_b32_e32 v65, v2
	v_mov_b32_e32 v66, v2
	v_mov_b32_e32 v67, v2
	v_mov_b32_e32 v68, v2
	v_mov_b32_e32 v69, v2
	v_mov_b32_e32 v70, v2
	v_mov_b32_e32 v71, v2
	v_mov_b32_e32 v72, v2
	v_mov_b32_e32 v73, v2
	v_mov_b32_e32 v82, v2
	v_mov_b32_e32 v83, v2
	v_mov_b32_e32 v84, v2
	v_mov_b32_e32 v85, v2
	v_mov_b32_e32 v86, v2
	v_mov_b32_e32 v87, v2
	v_mov_b32_e32 v88, v2
	v_mov_b32_e32 v89, v2
	v_mov_b32_e32 v98, v2
	v_mov_b32_e32 v99, v2
	v_mov_b32_e32 v100, v2
	v_mov_b32_e32 v101, v2
	v_mov_b32_e32 v102, v2
	v_mov_b32_e32 v103, v2
	v_mov_b32_e32 v104, v2
	v_mov_b32_e32 v105, v2
	v_mov_b32_e32 v114, v2
	v_mov_b32_e32 v115, v2
	v_mov_b32_e32 v116, v2
	v_mov_b32_e32 v117, v2
	v_mov_b32_e32 v118, v2
	v_mov_b32_e32 v119, v2
	v_mov_b32_e32 v120, v2
	v_mov_b32_e32 v121, v2
	v_mov_b32_e32 v74, v2
	v_mov_b32_e32 v75, v2
	v_mov_b32_e32 v76, v2
	v_mov_b32_e32 v77, v2
	v_mov_b32_e32 v78, v2
	v_mov_b32_e32 v79, v2
	v_mov_b32_e32 v80, v2
	v_mov_b32_e32 v81, v2
	v_mov_b32_e32 v90, v2
	v_mov_b32_e32 v91, v2
	v_mov_b32_e32 v92, v2
	v_mov_b32_e32 v93, v2
	v_mov_b32_e32 v94, v2
	v_mov_b32_e32 v95, v2
	v_mov_b32_e32 v96, v2
	v_mov_b32_e32 v97, v2
	v_mov_b32_e32 v106, v2
	v_mov_b32_e32 v107, v2
	v_mov_b32_e32 v108, v2
	v_mov_b32_e32 v109, v2
	v_mov_b32_e32 v110, v2
	v_mov_b32_e32 v111, v2
	v_mov_b32_e32 v112, v2
	v_mov_b32_e32 v113, v2
	v_mov_b32_e32 v122, v2
	v_mov_b32_e32 v123, v2
	v_mov_b32_e32 v124, v2
	v_mov_b32_e32 v125, v2
	v_mov_b32_e32 v126, v2
	v_mov_b32_e32 v127, v2
	v_mov_b32_e32 v128, v2
	v_mov_b32_e32 v129, v2

; __device__ __forceinline__ unsigned pk2(float lo, float hi) { return pg8::cvt_pk_bf16(lo, hi); }
;     __device__ __forceinline__ void operator()(const f32x4 (&acc)[2][2][4][2], const pg8::Unit& u, int wr, int wc, int fr, int fq) const {
;         const int row0 = u.pm * 256 + wr * 64 + fr, col0 = u.pn * 256 + wc * 32 + 8 * fq;
;         const int Rt = rowbase + u.pm * 256;
;         const float* bp = bias + (size_t)(Rt < TL ? (Rt >> 13) : 8) * FF2 + col0;
;         f32x4 bv[2][2];
; #pragma unroll
;         for (int bj = 0; bj < 2; ++bj) { bv[bj][0] = *(const f32x4*)(bp + bj * 128); bv[bj][1] = *(const f32x4*)(bp + bj * 128 + 4); }
; #pragma unroll
;         for (int ai = 0; ai < 2; ++ai)
; #pragma unroll
;             for (int m = 0; m < 4; ++m) { const int r = row0 + ai * 128 + m * 16, Rg = rowbase + r;
;                 const f32x4 q = *(const f32x4*)(stat + (size_t)Rg * 16 + fq * 4);
;                 float ssq = (q[0] + q[1]) + (q[2] + q[3]); ssq += __shfl_xor(ssq, 16); ssq += __shfl_xor(ssq, 32);
;                 const float rstd = rsqrtf(ssq * (1.f / DM) + 1e-6f);
;                 bf16_t* rowp = O + (size_t)r * ldc + col0;
; #pragma unroll
;                 for (int bj = 0; bj < 2; ++bj) { const f32x4 v0 = acc[ai][bj][m][0] * rstd + bv[bj][0], v1 = acc[ai][bj][m][1] * rstd + bv[bj][1];
;                     u32x4 w; w.x = pk2(v0[0], v0[1]); w.y = pk2(v0[2], v0[3]); w.z = pk2(v1[0], v1[1]); w.w = pk2(v1[2], v1[3]);
;                     *(u32x4*)(rowp + bj * 128) = w; } }
.LBB0_1278:
	s_lshl_b32 s10, s58, 8
	v_add_u32_e32 v176, s10, v178
	v_ashrrev_i32_e32 v177, 31, v176
	v_lshlrev_b64 v[130:131], 6, v[176:177]
	v_lshl_add_u64 v[130:131], v[152:153], 0, v[130:131]
	v_lshlrev_b32_e32 v194, 6, v178
	v_and_b32_e32 v195, 48, v163
	v_add_u32_e32 v194, v194, v195
	v_add_u32_e32 v194, 0x20010, v194
	ds_read_b128 v[158:161], v194
	ds_read_b128 v[196:199], v194 offset:1024
	ds_read_b128 v[200:203], v194 offset:2048
	ds_read_b128 v[204:207], v194 offset:3072
	ds_read_b128 v[208:211], v194 offset:8192
	ds_read_b128 v[212:215], v194 offset:9216
	ds_read_b128 v[216:219], v194 offset:10240
	ds_read_b128 v[220:223], v194 offset:11264
	s_min_i32 s10, s10, 0x10000
	s_ashr_i32 s10, s10, 13
	s_mulk_i32 s10, 0x1600
	s_ashr_i32 s11, s10, 31
	s_lshl_b64 s[10:11], s[10:11], 2
	v_lshl_or_b32 v184, s57, 8, v180
	s_add_u32 s10, s8, s10
	v_ashrrev_i32_e32 v185, 31, v184
	s_addc_u32 s11, s9, s11
	v_lshl_add_u64 v[130:131], v[184:185], 2, s[10:11]
	v_lshlrev_b32_e32 v195, 2, v180
	v_add_u32_e32 v195, 0x24010, v195
	ds_read_b128 v[142:145], v195
	ds_read_b128 v[138:141], v195 offset:16
	ds_read_b128 v[134:137], v195 offset:512
	ds_read_b128 v[130:133], v195 offset:528
	v_and_b32_e32 v182, 64, v228
	v_xor_b32_e32 v177, 16, v228
	v_add_u32_e32 v187, 64, v182
	v_cmp_lt_i32_e32 vcc, v177, v187
	v_xor_b32_e32 v186, 32, v228
	s_mov_b64 s[34:35], -1
	v_cndmask_b32_e32 v177, v228, v177, vcc
	v_lshlrev_b32_e32 v177, 2, v177
	v_cmp_lt_i32_e32 vcc, v186, v187
	s_waitcnt vmcnt(0) lgkmcnt(0)
	s_barrier
	v_lshlrev_b32_e32 v244, 4, v228
	v_readfirstlane_b32 s98, v163
	v_readfirstlane_b32 s100, v152
	v_readfirstlane_b32 s101, v153
	s_lshl_b32 s98, s98, 5
	s_lshl_b32 s99, 0, 6
	s_lshl_b32 s32, s71, 14
	s_add_i32 s99, s99, s32
	s_add_i32 s99, s99, s98
	s_add_u32 s100, s100, s99
	s_addc_u32 s101, s101, 0
	s_add_i32 m0, s98, 0x20010
	s_nop 0
	global_load_lds_dwordx4 v244, s[100:101]
	global_load_lds_dwordx4 v244, s[100:101] offset:1024
	s_lshl_b32 s99, s71, 8
	s_add_i32 s99, s99, 0
	s_min_i32 s99, s99, 0x10000
	s_ashr_i32 s99, s99, 13
	s_mulk_i32 s99, 0x1600
	s_lshl_b32 s99, s99, 2
	s_lshl_b32 s32, s72, 10
	s_add_i32 s99, s99, s32
	s_add_u32 s100, s8, s99
	s_addc_u32 s101, s9, 0
	s_mov_b32 m0, 0x24010
	s_nop 0
	global_load_lds_dwordx4 v244, s[100:101]
	v_mov_b32_e32 v182, v159
	v_mov_b32_e32 v183, v160
	v_mov_b32_e32 v159, v161
	v_pk_add_f32 v[158:159], v[182:183], v[158:159]
	v_cndmask_b32_e32 v182, v228, v186, vcc
	v_add_f32_e32 v160, v158, v159
	ds_bpermute_b32 v161, v177, v160
	v_lshlrev_b32_e32 v182, 2, v182
	v_mov_b64_e32 v[158:159], s[22:23]
	v_mad_i64_i32 v[186:187], s[10:11], v176, s83, v[158:159]
	s_waitcnt lgkmcnt(0)
	v_add_f32_e32 v183, v160, v161
	ds_bpermute_b32 v188, v182, v183
	v_lshlrev_b64 v[160:161], 1, v[184:185]
	v_or_b32_e32 v184, 16, v176
	v_lshl_add_u64 v[186:187], v[186:187], 0, v[160:161]
	s_waitcnt lgkmcnt(0)
	v_add_f32_e32 v183, v183, v188
	v_fmamk_f32 v183, v183, 0x3a800000, v162
	v_mul_f32_e32 v185, 0x4b800000, v183
	v_cmp_gt_f32_e32 vcc, s82, v183
	s_nop 1
	v_cndmask_b32_e32 v183, v183, v185, vcc
	v_rsq_f32_e32 v183, v183
	v_ashrrev_i32_e32 v185, 31, v184
	v_lshlrev_b64 v[188:189], 6, v[184:185]
	v_lshl_add_u64 v[188:189], v[152:153], 0, v[188:189]
	v_mul_f32_e32 v185, 0x45800000, v183
	v_cndmask_b32_e32 v190, v183, v185, vcc
	v_pk_fma_f32 v[128:129], v[128:129], v[190:191], v[144:145] op_sel_hi:[1,0,1]
	v_pk_fma_f32 v[126:127], v[126:127], v[190:191], v[142:143] op_sel_hi:[1,0,1]
	v_pk_fma_f32 v[124:125], v[124:125], v[190:191], v[140:141] op_sel_hi:[1,0,1]
	v_pk_fma_f32 v[122:123], v[122:123], v[190:191], v[138:139] op_sel_hi:[1,0,1]
	v_pk_fma_f32 v[120:121], v[120:121], v[190:191], v[136:137] op_sel_hi:[1,0,1]
	v_pk_fma_f32 v[118:119], v[118:119], v[190:191], v[134:135] op_sel_hi:[1,0,1]
	v_pk_fma_f32 v[192:193], v[116:117], v[190:191], v[132:133] op_sel_hi:[1,0,1]
	v_pk_fma_f32 v[190:191], v[114:115], v[190:191], v[130:131] op_sel_hi:[1,0,1]
	v_cvt_pk_bf16_f32 v114, v126, v127
	v_cvt_pk_bf16_f32 v115, v128, v129
	v_cvt_pk_bf16_f32 v116, v122, v123
	v_cvt_pk_bf16_f32 v117, v124, v125
	v_cvt_pk_bf16_f32 v118, v118, v119
	v_cvt_pk_bf16_f32 v119, v120, v121
	v_cvt_pk_bf16_f32 v120, v190, v191
	v_cvt_pk_bf16_f32 v121, v192, v193
	global_store_dwordx4 v[186:187], v[114:117], off
	global_store_dwordx4 v[186:187], v[118:121], off offset:256
	s_nop 1
	v_add_f32_e32 v114, v196, v197
	v_add_f32_e32 v115, v198, v199
	v_mad_i64_i32 v[116:117], s[10:11], v184, s83, v[158:159]
	v_add_f32_e32 v114, v114, v115
	ds_bpermute_b32 v115, v177, v114
	v_lshl_add_u64 v[116:117], v[116:117], 0, v[160:161]
	s_waitcnt lgkmcnt(0)
	v_add_f32_e32 v118, v114, v115
	ds_bpermute_b32 v119, v182, v118
	v_or_b32_e32 v114, 32, v176
	v_ashrrev_i32_e32 v115, 31, v114
	s_waitcnt lgkmcnt(0)
	v_add_f32_e32 v118, v118, v119
	v_fmamk_f32 v118, v118, 0x3a800000, v162
	v_mul_f32_e32 v119, 0x4b800000, v118
	v_cmp_gt_f32_e32 vcc, s82, v118
	s_nop 1
	v_cndmask_b32_e32 v118, v118, v119, vcc
	v_rsq_f32_e32 v120, v118
	v_lshlrev_b64 v[118:119], 6, v[114:115]
	v_lshl_add_u64 v[118:119], v[152:153], 0, v[118:119]
	v_mul_f32_e32 v115, 0x45800000, v120
	v_cndmask_b32_e32 v120, v120, v115, vcc
	v_pk_fma_f32 v[112:113], v[112:113], v[120:121], v[144:145] op_sel_hi:[1,0,1]
	v_pk_fma_f32 v[110:111], v[110:111], v[120:121], v[142:143] op_sel_hi:[1,0,1]
	v_pk_fma_f32 v[108:109], v[108:109], v[120:121], v[140:141] op_sel_hi:[1,0,1]
	v_pk_fma_f32 v[106:107], v[106:107], v[120:121], v[138:139] op_sel_hi:[1,0,1]
	v_pk_fma_f32 v[104:105], v[104:105], v[120:121], v[136:137] op_sel_hi:[1,0,1]
	v_pk_fma_f32 v[102:103], v[102:103], v[120:121], v[134:135] op_sel_hi:[1,0,1]
	v_pk_fma_f32 v[122:123], v[100:101], v[120:121], v[132:133] op_sel_hi:[1,0,1]
	v_pk_fma_f32 v[120:121], v[98:99], v[120:121], v[130:131] op_sel_hi:[1,0,1]
	v_cvt_pk_bf16_f32 v98, v110, v111
	v_cvt_pk_bf16_f32 v99, v112, v113
	v_cvt_pk_bf16_f32 v100, v106, v107
	v_cvt_pk_bf16_f32 v101, v108, v109
	v_cvt_pk_bf16_f32 v102, v102, v103
	v_cvt_pk_bf16_f32 v103, v104, v105
	v_cvt_pk_bf16_f32 v104, v120, v121
	v_cvt_pk_bf16_f32 v105, v122, v123
	global_store_dwordx4 v[116:117], v[98:101], off
	global_store_dwordx4 v[116:117], v[102:105], off offset:256
	s_nop 1
	v_add_f32_e32 v98, v200, v201
	v_add_f32_e32 v99, v202, v203
	v_mad_i64_i32 v[100:101], s[10:11], v114, s83, v[158:159]
	v_add_f32_e32 v98, v98, v99
	ds_bpermute_b32 v99, v177, v98
	v_lshl_add_u64 v[100:101], v[100:101], 0, v[160:161]
	s_waitcnt lgkmcnt(0)
; __device__ __forceinline__ unsigned pk2(float lo, float hi) { return pg8::cvt_pk_bf16(lo, hi); }
;     __device__ __forceinline__ void operator()(const f32x4 (&acc)[2][2][4][2], const pg8::Unit& u, int wr, int wc, int fr, int fq) const {
;     ...
;             for (int m = 0; m < 4; ++m) { const int r = row0 + ai * 128 + m * 16, Rg = rowbase + r;
;                 const f32x4 q = *(const f32x4*)(stat + (size_t)Rg * 16 + fq * 4);
;                 float ssq = (q[0] + q[1]) + (q[2] + q[3]); ssq += __shfl_xor(ssq, 16); ssq += __shfl_xor(ssq, 32);
;                 const float rstd = rsqrtf(ssq * (1.f / DM) + 1e-6f);
;                 bf16_t* rowp = O + (size_t)r * ldc + col0;
; #pragma unroll
;                 for (int bj = 0; bj < 2; ++bj) { const f32x4 v0 = acc[ai][bj][m][0] * rstd + bv[bj][0], v1 = acc[ai][bj][m][1] * rstd + bv[bj][1];
;                     u32x4 w; w.x = pk2(v0[0], v0[1]); w.y = pk2(v0[2], v0[3]); w.z = pk2(v1[0], v1[1]); w.w = pk2(v1[2], v1[3]);
;                     *(u32x4*)(rowp + bj * 128) = w; } }
	v_add_f32_e32 v102, v98, v99
	ds_bpermute_b32 v103, v182, v102
	v_or_b32_e32 v98, 48, v176
	v_ashrrev_i32_e32 v99, 31, v98
	s_waitcnt lgkmcnt(0)
	v_add_f32_e32 v102, v102, v103
	v_fmamk_f32 v102, v102, 0x3a800000, v162
	v_mul_f32_e32 v103, 0x4b800000, v102
	v_cmp_gt_f32_e32 vcc, s82, v102
	s_nop 1
	v_cndmask_b32_e32 v102, v102, v103, vcc
	v_rsq_f32_e32 v104, v102
	v_lshlrev_b64 v[102:103], 6, v[98:99]
	v_lshl_add_u64 v[102:103], v[152:153], 0, v[102:103]
	v_mul_f32_e32 v99, 0x45800000, v104
	v_cndmask_b32_e32 v104, v104, v99, vcc
	v_pk_fma_f32 v[96:97], v[96:97], v[104:105], v[144:145] op_sel_hi:[1,0,1]
	v_pk_fma_f32 v[94:95], v[94:95], v[104:105], v[142:143] op_sel_hi:[1,0,1]
	v_pk_fma_f32 v[92:93], v[92:93], v[104:105], v[140:141] op_sel_hi:[1,0,1]
	v_pk_fma_f32 v[90:91], v[90:91], v[104:105], v[138:139] op_sel_hi:[1,0,1]
	v_pk_fma_f32 v[88:89], v[88:89], v[104:105], v[136:137] op_sel_hi:[1,0,1]
	v_pk_fma_f32 v[86:87], v[86:87], v[104:105], v[134:135] op_sel_hi:[1,0,1]
	v_pk_fma_f32 v[106:107], v[84:85], v[104:105], v[132:133] op_sel_hi:[1,0,1]
	v_pk_fma_f32 v[104:105], v[82:83], v[104:105], v[130:131] op_sel_hi:[1,0,1]
	v_cvt_pk_bf16_f32 v82, v94, v95
	v_cvt_pk_bf16_f32 v83, v96, v97
	v_cvt_pk_bf16_f32 v84, v90, v91
	v_cvt_pk_bf16_f32 v85, v92, v93
	v_cvt_pk_bf16_f32 v86, v86, v87
	v_cvt_pk_bf16_f32 v87, v88, v89
	v_cvt_pk_bf16_f32 v88, v104, v105
	v_cvt_pk_bf16_f32 v89, v106, v107
	global_store_dwordx4 v[100:101], v[82:85], off
	global_store_dwordx4 v[100:101], v[86:89], off offset:256
	s_nop 1
	v_add_f32_e32 v82, v204, v205
	v_add_f32_e32 v83, v206, v207
	v_mad_i64_i32 v[84:85], s[10:11], v98, s83, v[158:159]
	v_add_f32_e32 v82, v82, v83
	ds_bpermute_b32 v83, v177, v82
	v_lshl_add_u64 v[84:85], v[84:85], 0, v[160:161]
	s_waitcnt lgkmcnt(0)
	v_add_f32_e32 v86, v82, v83
	ds_bpermute_b32 v87, v182, v86
	v_add_u32_e32 v82, 0x80, v176
	v_ashrrev_i32_e32 v83, 31, v82
	s_waitcnt lgkmcnt(0)
	v_add_f32_e32 v86, v86, v87
	v_fmamk_f32 v86, v86, 0x3a800000, v162
	v_mul_f32_e32 v87, 0x4b800000, v86
	v_cmp_gt_f32_e32 vcc, s82, v86
	s_nop 1
	v_cndmask_b32_e32 v86, v86, v87, vcc
	v_rsq_f32_e32 v88, v86
	v_lshlrev_b64 v[86:87], 6, v[82:83]
	v_lshl_add_u64 v[86:87], v[152:153], 0, v[86:87]
	v_mul_f32_e32 v83, 0x45800000, v88
	v_cndmask_b32_e32 v88, v88, v83, vcc
	v_pk_fma_f32 v[80:81], v[80:81], v[88:89], v[144:145] op_sel_hi:[1,0,1]
	v_pk_fma_f32 v[78:79], v[78:79], v[88:89], v[142:143] op_sel_hi:[1,0,1]
	v_pk_fma_f32 v[76:77], v[76:77], v[88:89], v[140:141] op_sel_hi:[1,0,1]
	v_pk_fma_f32 v[74:75], v[74:75], v[88:89], v[138:139] op_sel_hi:[1,0,1]
	v_pk_fma_f32 v[72:73], v[72:73], v[88:89], v[136:137] op_sel_hi:[1,0,1]
	v_pk_fma_f32 v[70:71], v[70:71], v[88:89], v[134:135] op_sel_hi:[1,0,1]
	v_pk_fma_f32 v[90:91], v[68:69], v[88:89], v[132:133] op_sel_hi:[1,0,1]
	v_pk_fma_f32 v[88:89], v[66:67], v[88:89], v[130:131] op_sel_hi:[1,0,1]
	v_cvt_pk_bf16_f32 v66, v78, v79
	v_cvt_pk_bf16_f32 v67, v80, v81
	v_cvt_pk_bf16_f32 v68, v74, v75
	v_cvt_pk_bf16_f32 v69, v76, v77
	v_cvt_pk_bf16_f32 v70, v70, v71
	v_cvt_pk_bf16_f32 v71, v72, v73
	v_cvt_pk_bf16_f32 v72, v88, v89
	v_cvt_pk_bf16_f32 v73, v90, v91
	global_store_dwordx4 v[84:85], v[66:69], off
	global_store_dwordx4 v[84:85], v[70:73], off offset:256
	s_nop 1
	v_add_f32_e32 v66, v208, v209
	v_add_f32_e32 v67, v210, v211
	v_mad_i64_i32 v[68:69], s[10:11], v82, s83, v[158:159]
	v_add_f32_e32 v66, v66, v67
	ds_bpermute_b32 v67, v177, v66
	v_lshl_add_u64 v[68:69], v[68:69], 0, v[160:161]
	s_waitcnt lgkmcnt(0)
	v_add_f32_e32 v70, v66, v67
	ds_bpermute_b32 v71, v182, v70
	v_add_u32_e32 v66, 0x90, v176
	v_ashrrev_i32_e32 v67, 31, v66
	s_waitcnt lgkmcnt(0)
	v_add_f32_e32 v70, v70, v71
	v_fmamk_f32 v70, v70, 0x3a800000, v162
	v_mul_f32_e32 v71, 0x4b800000, v70
	v_cmp_gt_f32_e32 vcc, s82, v70
	s_nop 1
	v_cndmask_b32_e32 v70, v70, v71, vcc
	v_rsq_f32_e32 v72, v70
	v_lshlrev_b64 v[70:71], 6, v[66:67]
	v_lshl_add_u64 v[70:71], v[152:153], 0, v[70:71]
	v_mul_f32_e32 v67, 0x45800000, v72
	v_cndmask_b32_e32 v72, v72, v67, vcc
	v_pk_fma_f32 v[64:65], v[64:65], v[72:73], v[144:145] op_sel_hi:[1,0,1]
	v_pk_fma_f32 v[62:63], v[62:63], v[72:73], v[142:143] op_sel_hi:[1,0,1]
	v_pk_fma_f32 v[60:61], v[60:61], v[72:73], v[140:141] op_sel_hi:[1,0,1]
	v_pk_fma_f32 v[58:59], v[58:59], v[72:73], v[138:139] op_sel_hi:[1,0,1]
	v_pk_fma_f32 v[56:57], v[56:57], v[72:73], v[136:137] op_sel_hi:[1,0,1]
	v_pk_fma_f32 v[54:55], v[54:55], v[72:73], v[134:135] op_sel_hi:[1,0,1]
	v_pk_fma_f32 v[74:75], v[52:53], v[72:73], v[132:133] op_sel_hi:[1,0,1]
	v_pk_fma_f32 v[72:73], v[50:51], v[72:73], v[130:131] op_sel_hi:[1,0,1]
	v_cvt_pk_bf16_f32 v50, v62, v63
	v_cvt_pk_bf16_f32 v51, v64, v65
	v_cvt_pk_bf16_f32 v52, v58, v59
	v_cvt_pk_bf16_f32 v53, v60, v61
	v_cvt_pk_bf16_f32 v54, v54, v55
	v_cvt_pk_bf16_f32 v55, v56, v57
	v_cvt_pk_bf16_f32 v56, v72, v73
	v_cvt_pk_bf16_f32 v57, v74, v75
	global_store_dwordx4 v[68:69], v[50:53], off
	global_store_dwordx4 v[68:69], v[54:57], off offset:256
	s_nop 1
	v_add_f32_e32 v50, v212, v213
	v_add_f32_e32 v51, v214, v215
	v_mad_i64_i32 v[52:53], s[10:11], v66, s83, v[158:159]
	v_add_f32_e32 v50, v50, v51
	ds_bpermute_b32 v51, v177, v50
	v_lshl_add_u64 v[52:53], v[52:53], 0, v[160:161]
	s_waitcnt lgkmcnt(0)
; __device__ __forceinline__ unsigned pk2(float lo, float hi) { return pg8::cvt_pk_bf16(lo, hi); }
;     __device__ __forceinline__ void operator()(const f32x4 (&acc)[2][2][4][2], const pg8::Unit& u, int wr, int wc, int fr, int fq) const {
;     ...
;             for (int m = 0; m < 4; ++m) { const int r = row0 + ai * 128 + m * 16, Rg = rowbase + r;
;                 const f32x4 q = *(const f32x4*)(stat + (size_t)Rg * 16 + fq * 4);
;                 float ssq = (q[0] + q[1]) + (q[2] + q[3]); ssq += __shfl_xor(ssq, 16); ssq += __shfl_xor(ssq, 32);
;                 const float rstd = rsqrtf(ssq * (1.f / DM) + 1e-6f);
;                 bf16_t* rowp = O + (size_t)r * ldc + col0;
; #pragma unroll
;                 for (int bj = 0; bj < 2; ++bj) { const f32x4 v0 = acc[ai][bj][m][0] * rstd + bv[bj][0], v1 = acc[ai][bj][m][1] * rstd + bv[bj][1];
;                     u32x4 w; w.x = pk2(v0[0], v0[1]); w.y = pk2(v0[2], v0[3]); w.z = pk2(v1[0], v1[1]); w.w = pk2(v1[2], v1[3]);
;                     *(u32x4*)(rowp + bj * 128) = w; } }
	v_add_f32_e32 v54, v50, v51
	ds_bpermute_b32 v55, v182, v54
	v_add_u32_e32 v50, 0xa0, v176
	v_ashrrev_i32_e32 v51, 31, v50
	s_waitcnt lgkmcnt(0)
	v_add_f32_e32 v54, v54, v55
	v_fmamk_f32 v54, v54, 0x3a800000, v162
	v_mul_f32_e32 v55, 0x4b800000, v54
	v_cmp_gt_f32_e32 vcc, s82, v54
	s_nop 1
	v_cndmask_b32_e32 v54, v54, v55, vcc
	v_rsq_f32_e32 v56, v54
	v_lshlrev_b64 v[54:55], 6, v[50:51]
	v_lshl_add_u64 v[54:55], v[152:153], 0, v[54:55]
	v_mul_f32_e32 v51, 0x45800000, v56
	v_cndmask_b32_e32 v56, v56, v51, vcc
	v_pk_fma_f32 v[48:49], v[48:49], v[56:57], v[144:145] op_sel_hi:[1,0,1]
	v_pk_fma_f32 v[46:47], v[46:47], v[56:57], v[142:143] op_sel_hi:[1,0,1]
	v_pk_fma_f32 v[44:45], v[44:45], v[56:57], v[140:141] op_sel_hi:[1,0,1]
	v_pk_fma_f32 v[42:43], v[42:43], v[56:57], v[138:139] op_sel_hi:[1,0,1]
	v_pk_fma_f32 v[40:41], v[40:41], v[56:57], v[136:137] op_sel_hi:[1,0,1]
	v_pk_fma_f32 v[38:39], v[38:39], v[56:57], v[134:135] op_sel_hi:[1,0,1]
	v_pk_fma_f32 v[58:59], v[36:37], v[56:57], v[132:133] op_sel_hi:[1,0,1]
	v_pk_fma_f32 v[56:57], v[34:35], v[56:57], v[130:131] op_sel_hi:[1,0,1]
	v_cvt_pk_bf16_f32 v34, v46, v47
	v_cvt_pk_bf16_f32 v35, v48, v49
	v_cvt_pk_bf16_f32 v36, v42, v43
	v_cvt_pk_bf16_f32 v37, v44, v45
	v_cvt_pk_bf16_f32 v38, v38, v39
	v_cvt_pk_bf16_f32 v39, v40, v41
	v_cvt_pk_bf16_f32 v40, v56, v57
	v_cvt_pk_bf16_f32 v41, v58, v59
	global_store_dwordx4 v[52:53], v[34:37], off
	global_store_dwordx4 v[52:53], v[38:41], off offset:256
	s_nop 1
	v_add_f32_e32 v34, v216, v217
	v_add_f32_e32 v35, v218, v219
	v_mad_i64_i32 v[36:37], s[10:11], v50, s83, v[158:159]
	v_add_f32_e32 v34, v34, v35
	ds_bpermute_b32 v35, v177, v34
	v_lshl_add_u64 v[36:37], v[36:37], 0, v[160:161]
	s_waitcnt lgkmcnt(0)
	v_add_f32_e32 v38, v34, v35
	ds_bpermute_b32 v39, v182, v38
	v_add_u32_e32 v34, 0xb0, v176
	v_ashrrev_i32_e32 v35, 31, v34
	s_waitcnt lgkmcnt(0)
	v_add_f32_e32 v38, v38, v39
	v_fmamk_f32 v38, v38, 0x3a800000, v162
	v_mul_f32_e32 v39, 0x4b800000, v38
	v_cmp_gt_f32_e32 vcc, s82, v38
	s_nop 1
	v_cndmask_b32_e32 v38, v38, v39, vcc
	v_rsq_f32_e32 v40, v38
	v_lshlrev_b64 v[38:39], 6, v[34:35]
	v_lshl_add_u64 v[38:39], v[152:153], 0, v[38:39]
	v_mul_f32_e32 v35, 0x45800000, v40
	v_cndmask_b32_e32 v40, v40, v35, vcc
	v_pk_fma_f32 v[32:33], v[32:33], v[40:41], v[144:145] op_sel_hi:[1,0,1]
	v_pk_fma_f32 v[30:31], v[30:31], v[40:41], v[142:143] op_sel_hi:[1,0,1]
	v_pk_fma_f32 v[28:29], v[28:29], v[40:41], v[140:141] op_sel_hi:[1,0,1]
	v_pk_fma_f32 v[26:27], v[26:27], v[40:41], v[138:139] op_sel_hi:[1,0,1]
	v_pk_fma_f32 v[24:25], v[24:25], v[40:41], v[136:137] op_sel_hi:[1,0,1]
	v_pk_fma_f32 v[22:23], v[22:23], v[40:41], v[134:135] op_sel_hi:[1,0,1]
	v_pk_fma_f32 v[42:43], v[20:21], v[40:41], v[132:133] op_sel_hi:[1,0,1]
	v_pk_fma_f32 v[40:41], v[18:19], v[40:41], v[130:131] op_sel_hi:[1,0,1]
	v_cvt_pk_bf16_f32 v18, v30, v31
	v_cvt_pk_bf16_f32 v19, v32, v33
	v_cvt_pk_bf16_f32 v20, v26, v27
	v_cvt_pk_bf16_f32 v21, v28, v29
	v_cvt_pk_bf16_f32 v22, v22, v23
	v_cvt_pk_bf16_f32 v23, v24, v25
	v_cvt_pk_bf16_f32 v24, v40, v41
	v_cvt_pk_bf16_f32 v25, v42, v43
	global_store_dwordx4 v[36:37], v[18:21], off
	global_store_dwordx4 v[36:37], v[22:25], off offset:256
	s_andn2_b64 vcc, exec, s[38:39]
	s_nop 1
	v_add_f32_e32 v18, v220, v221
	v_add_f32_e32 v19, v222, v223
	s_nop 0
	v_add_f32_e32 v18, v18, v19
	ds_bpermute_b32 v19, v177, v18
	s_waitcnt lgkmcnt(0)
	v_add_f32_e32 v18, v18, v19
	ds_bpermute_b32 v19, v182, v18
	s_waitcnt lgkmcnt(0)
	v_add_f32_e32 v18, v18, v19
	v_fmamk_f32 v18, v18, 0x3a800000, v162
	v_mul_f32_e32 v19, 0x4b800000, v18
	v_cmp_gt_f32_e64 s[40:41], s82, v18
	s_nop 1
	v_cndmask_b32_e64 v18, v18, v19, s[40:41]
	v_rsq_f32_e32 v20, v18
	v_mad_i64_i32 v[18:19], s[10:11], v34, s83, v[158:159]
	v_lshl_add_u64 v[18:19], v[18:19], 0, v[160:161]
	v_mul_f32_e32 v21, 0x45800000, v20
	v_cndmask_b32_e64 v20, v20, v21, s[40:41]
	v_pk_fma_f32 v[16:17], v[16:17], v[20:21], v[144:145] op_sel_hi:[1,0,1]
	v_pk_fma_f32 v[14:15], v[14:15], v[20:21], v[142:143] op_sel_hi:[1,0,1]
	v_pk_fma_f32 v[12:13], v[12:13], v[20:21], v[140:141] op_sel_hi:[1,0,1]
	v_pk_fma_f32 v[10:11], v[10:11], v[20:21], v[138:139] op_sel_hi:[1,0,1]
	v_pk_fma_f32 v[8:9], v[8:9], v[20:21], v[136:137] op_sel_hi:[1,0,1]
	v_pk_fma_f32 v[6:7], v[6:7], v[20:21], v[134:135] op_sel_hi:[1,0,1]
	v_pk_fma_f32 v[22:23], v[4:5], v[20:21], v[132:133] op_sel_hi:[1,0,1]
	v_pk_fma_f32 v[20:21], v[2:3], v[20:21], v[130:131] op_sel_hi:[1,0,1]
	v_cvt_pk_bf16_f32 v2, v14, v15
	v_cvt_pk_bf16_f32 v3, v16, v17
	v_cvt_pk_bf16_f32 v4, v10, v11
	v_cvt_pk_bf16_f32 v5, v12, v13
	v_cvt_pk_bf16_f32 v6, v6, v7
	v_cvt_pk_bf16_f32 v7, v8, v9
	v_cvt_pk_bf16_f32 v8, v20, v21
	v_cvt_pk_bf16_f32 v9, v22, v23
	global_store_dwordx4 v[18:19], v[2:5], off
	global_store_dwordx4 v[18:19], v[6:9], off offset:256
	s_cbranch_vccnz .LBB0_1271
	s_andn2_b64 vcc, exec, s[20:21]
	s_cbranch_vccnz .LBB0_1270
	s_barrier
	s_branch .LBB0_1270
